# P4b scan workgroups: prompt scan first, sample sequences afterwards (less memory interference with the streaming workgroups at phase start)
# speedup vs baseline: 1.0058x; 1.0058x over previous
; __device__ __forceinline__ void hg_seq(const Frame& F, unsigned char* ws, const float* s0, float* sout, float* Og, int seq, bool sample, int vs_base, int nvs) {
;     LAS unsigned char* ring = F.lds;
;     const int tid = F.tid, lane = F.lane, vs = vs_base + F.wave, r = lane & 15, q = lane >> 4;
;     const bool active = F.wave < nvs, vload = (unsigned)((tid >> 6) - vs_base) < (unsigned)nvs;
;     int nch, nvalid, t0, h; const unsigned char *qf, *vf, *lf; int qp, lp; size_t qstep, lstep;
;     if (!sample) { const int b = seq >> 2; h = seq & 3; t0 = b * 2048; nch = 64; nvalid = 32; const size_t e0 = (size_t)t0 * DA + h * 128;
;         qf = ws + WS_Q + e0 * 2; vf = ws + WS_V + e0 * 2; lf = ws + WS_LOGF + e0 * 4; qp = 1024; lp = 2048; qstep = 32 * 1024; lstep = 32 * 2048; }
;     else { const int b = seq >> 2; h = seq & 3; t0 = TP + b * 8; nch = 1; nvalid = 8; const unsigned char* base = (const unsigned char*)sout + (size_t)seq * 65536;
;         qf = base; vf = base + 8192; lf = base + 16384; qp = 256; lp = 512; qstep = 0; lstep = 0; }
;     const size_t offq = (size_t)(tid >> 4) * qp + (tid & 15) * 16, offl0 = (size_t)(tid >> 5) * lp + (tid & 31) * 16, offl1 = (size_t)(16 + (tid >> 5)) * lp + (tid & 31) * 16, offl1c = tid < 160 ? offl1 : offl0;
;     {
;     f32x4 S[8];
;     if (sample && active) {
; #pragma unroll
;         for (int kb = 0; kb < 8; ++kb)
; #pragma unroll
;             for (int i = 0; i < 4; ++i) S[kb][i] = s0[((size_t)seq * 128 + 16 * kb + 4 * q + i) * 128 + 16 * vs + r];
;     } else {
; #pragma unroll
;         for (int kb = 0; kb < 8; ++kb) S[kb] = (f32x4){0.f, 0.f, 0.f, 0.f};
;     }
;     float* Ob = Og + (size_t)t0 * DA + h * 128;
;     ...
;     HgPre R0, R1, R2, R3, R4, R5;
;     R0.l1 = R0.v = (v4u){0u, 0u, 0u, 0u}; R1.l1 = R1.v = (v4u){0u, 0u, 0u, 0u}; R2.l1 = R2.v = (v4u){0u, 0u, 0u, 0u}; R3.l1 = R3.v = (v4u){0u, 0u, 0u, 0u}; R4.l1 = R4.v = (v4u){0u, 0u, 0u, 0u}; R5.l1 = R5.v = (v4u){0u, 0u, 0u, 0u};
;     HG_LOAD(R0, 0); HG_LOAD(R1, 1); HG_LOAD(R2, 2); HG_LOAD(R3, 3); HG_LOAD(R4, 4);
;     HG_STORE(R0, 0); LDSBAR();
; __global__ void __launch_bounds__(NWAVES * 64, 2) mk_fwd(Args args) {
;     ...
;         if (G >= 2 * NSCAN) {
;             for (int s = bid; s < NSEQ_S; s += G) hg_seq(F, ws, st_h, out + OUT_SHS, Og, s, true, 0, 8);
;             if (bid < NSCAN) hg_seq(F, ws, nullptr, out + OUT_SHP, Og, bid >> 2, false, 2 * (bid & 3), 2);
.LBB0_1113:
	s_and_b64 vcc, exec, s[6:7]
	s_cbranch_vccz .LBB0_1246
	s_cmpk_gt_i32 s2, 0x7f
	v_and_b32_e32 v162, 15, v189
	s_waitcnt vmcnt(3)
	v_ashrrev_i32_e32 v52, 4, v188
	v_lshlrev_b32_e32 v101, 4, v188
	v_ashrrev_i32_e32 v50, 5, v188
	v_lshrrev_b32_e32 v100, 2, v189
	v_lshlrev_b32_e32 v98, 4, v189
	v_and_b32_e32 v99, 48, v189
	s_cbranch_scc1 .LBB0_1139
	s_branch .Lscan_entry
.Lsmp_entry:
	s_load_dwordx2 s[16:17], s[0:1], 0x10
	s_mov_b64 exec, -1
	s_waitcnt lgkmcnt(0)
	s_lshl_b32 s3, s2, 16
	s_add_u32 s8, s16, s3
	s_addc_u32 s9, s17, 0
	s_add_u32 s10, s20, 0x4608000
	s_addc_u32 s11, s21, 0
	s_add_u32 s10, s10, s3
	s_addc_u32 s11, s11, 0
	s_lshr_b32 s6, s2, 2
	s_lshl_b32 s6, s6, 14
	s_and_b32 s7, s2, 3
	s_lshl_b32 s7, s7, 9
	s_add_i32 s6, s6, s7
	s_add_u32 s12, s22, 0x4080000
	s_addc_u32 s13, s23, 0
	s_add_u32 s12, s12, s6
	s_addc_u32 s13, s13, 0
	s_mov_b32 s34, 0x800000
	s_mov_b32 s35, 0
	v_lshlrev_b32_e32 v142, 4, v189
	s_lshl_b32 s3, s50, 10
	v_add_u32_e32 v143, s3, v142
	v_lshrrev_b32_e32 v1, 4, v189
	v_lshlrev_b32_e32 v144, 4, v1
	s_lshl_b32 s3, s50, 4
	v_and_b32_e32 v2, 15, v189
	v_add_u32_e32 v2, s3, v2
	v_lshlrev_b32_e32 v2, 2, v2
	v_lshl_add_u32 v208, v1, 13, v2
	v_add_u32_e32 v209, 0x1000, v208
	v_and_b32_e32 v3, 3, v189
	v_lshlrev_b32_e32 v3, 9, v3
	v_lshl_add_u32 v3, v1, 11, v3
	v_bfe_u32 v200, v189, 2, 2
	v_lshl_add_u32 v3, v200, 4, v3
	s_lshl_b32 s3, s50, 6
	v_add_u32_e32 v200, s3, v3
	v_add_u32_e32 v201, 0x2000, v200
	v_add_u32_e32 v202, 0x4000, v200
	v_add_u32_e32 v203, 0x6000, v200
	v_add_u32_e32 v204, 0x8000, v200
	v_add_u32_e32 v205, 0xa000, v200
	v_add_u32_e32 v206, 0xc000, v200
	v_add_u32_e32 v207, 0xe000, v200
	s_mov_b32 s42, 0x55555555
	s_mov_b32 s43, 0x55555555
	s_mov_b32 s44, 0x33333333
	s_mov_b32 s45, 0x33333333
	v_mov_b32_e32 v3, 0
	v_mov_b32_e32 v2, v143
	v_lshl_add_u64 v[210:211], s[10:11], 0, v[2:3]
	s_add_u32 s6, s10, 0x2000
	s_addc_u32 s7, s11, 0
	v_lshl_add_u64 v[212:213], s[6:7], 0, v[2:3]
	s_add_u32 s6, s10, 0x4000
	s_addc_u32 s7, s11, 0
	v_lshl_add_u64 v[214:215], s[6:7], 0, v[2:3]
	s_mov_b32 s36, 0
	s_lshl_b32 s37, s50, 10
	s_cmp_lt_u32 s50, 3
	s_cbranch_scc0 .Lsmp_p4_done
	s_movk_i32 s36, 0x6000
	s_add_i32 s37, s37, 0x6000
.Lsmp_p4_done:
	s_add_u32 s6, s10, s36
	s_addc_u32 s7, s11, 0
	v_lshl_add_u64 v[140:141], s[6:7], 0, v[2:3]
	s_lshl_b32 s38, s50, 10
	s_add_i32 s39, s38, 0x4000
	s_add_i32 s40, s38, 0x2000
	s_mov_b32 m0, s38
	s_nop 0
	global_load_lds_dwordx4 v[210:211], off
	s_mov_b32 m0, s39
	s_nop 0
	global_load_lds_dwordx4 v[212:213], off
	s_mov_b32 m0, s40
	s_nop 0
	global_load_lds_dwordx4 v[214:215], off
	s_mov_b32 m0, s37
	s_nop 0
	global_load_lds_dwordx4 v[140:141], off
	v_lshl_add_u64 v[210:211], v[210:211], 0, s[34:35]
	v_lshl_add_u64 v[212:213], v[212:213], 0, s[34:35]
	v_lshl_add_u64 v[214:215], v[214:215], 0, s[34:35]
	v_lshl_add_u64 v[140:141], v[140:141], 0, s[34:35]
	s_add_i32 m0, s38, 0x6c00
	s_nop 0
	global_load_lds_dwordx4 v[210:211], off
	s_add_i32 m0, s39, 0x6c00
	s_nop 0
	global_load_lds_dwordx4 v[212:213], off
	s_add_i32 m0, s40, 0x6c00
	s_nop 0
	global_load_lds_dwordx4 v[214:215], off
	s_add_i32 m0, s37, 0x6c00
	s_nop 0
	global_load_lds_dwordx4 v[140:141], off
	v_lshl_add_u64 v[210:211], v[210:211], 0, s[34:35]
	v_lshl_add_u64 v[212:213], v[212:213], 0, s[34:35]
	v_lshl_add_u64 v[214:215], v[214:215], 0, s[34:35]
	v_lshl_add_u64 v[140:141], v[140:141], 0, s[34:35]
	s_add_i32 m0, s38, 0xd800
	s_nop 0
	global_load_lds_dwordx4 v[210:211], off
	s_add_i32 m0, s39, 0xd800
	s_nop 0
	global_load_lds_dwordx4 v[212:213], off
	s_add_i32 m0, s40, 0xd800
	s_nop 0
	global_load_lds_dwordx4 v[214:215], off
	s_add_i32 m0, s37, 0xd800
	s_nop 0
	global_load_lds_dwordx4 v[140:141], off
	v_lshl_add_u64 v[210:211], v[210:211], 0, s[34:35]
	v_lshl_add_u64 v[212:213], v[212:213], 0, s[34:35]
	v_lshl_add_u64 v[214:215], v[214:215], 0, s[34:35]
	v_lshl_add_u64 v[140:141], v[140:141], 0, s[34:35]
	s_add_i32 m0, s38, 0x14400
	s_nop 0
	global_load_lds_dwordx4 v[210:211], off
	s_add_i32 m0, s39, 0x14400
	s_nop 0
	global_load_lds_dwordx4 v[212:213], off
	s_add_i32 m0, s40, 0x14400
	s_nop 0
	global_load_lds_dwordx4 v[214:215], off
	s_add_i32 m0, s37, 0x14400
	s_nop 0
	global_load_lds_dwordx4 v[140:141], off
	global_load_dwordx4 v[4:7], v200, s[8:9]
	global_load_dwordx4 v[8:11], v201, s[8:9]
	global_load_dwordx4 v[12:15], v202, s[8:9]
	global_load_dwordx4 v[16:19], v203, s[8:9]
	global_load_dwordx4 v[20:23], v204, s[8:9]
	global_load_dwordx4 v[24:27], v205, s[8:9]
	global_load_dwordx4 v[28:31], v206, s[8:9]
	global_load_dwordx4 v[32:35], v207, s[8:9]
	s_add_u32 s8, s8, s34
	s_addc_u32 s9, s9, 0
	global_load_dwordx4 v[36:39], v200, s[8:9]
	global_load_dwordx4 v[40:43], v201, s[8:9]
	global_load_dwordx4 v[44:47], v202, s[8:9]
	global_load_dwordx4 v[48:51], v203, s[8:9]
	global_load_dwordx4 v[52:55], v204, s[8:9]
	global_load_dwordx4 v[56:59], v205, s[8:9]
	global_load_dwordx4 v[60:63], v206, s[8:9]
	global_load_dwordx4 v[64:67], v207, s[8:9]
	s_add_u32 s8, s8, s34
	s_addc_u32 s9, s9, 0
	s_waitcnt vmcnt(8)
	s_barrier
; __device__ __forceinline__ void hg_seq(const Frame& F, unsigned char* ws, const float* s0, float* sout, float* Og, int seq, bool sample, int vs_base, int nvs) {
;     ...
;     if (sample && active) {
; #pragma unroll
;         for (int kb = 0; kb < 8; ++kb)
; #pragma unroll
;             for (int i = 0; i < 4; ++i) S[kb][i] = s0[((size_t)seq * 128 + 16 * kb + 4 * q + i) * 128 + 16 * vs + r];
;     } else {
	v_cndmask_b32_e64 v145, v4, v5, s[42:43]
	v_cndmask_b32_e64 v147, v6, v7, s[42:43]
	s_nop 1
	v_mov_b32_dpp v146, v145 quad_perm:[1,0,3,2] row_mask:0xf bank_mask:0xf
	v_mov_b32_dpp v156, v147 quad_perm:[1,0,3,2] row_mask:0xf bank_mask:0xf
	v_cndmask_b32_e64 v5, v5, v146, s[42:43]
	v_cndmask_b32_e64 v4, v146, v4, s[42:43]
	v_cndmask_b32_e64 v7, v7, v156, s[42:43]
	v_cndmask_b32_e64 v6, v156, v6, s[42:43]
	v_cndmask_b32_e64 v145, v4, v6, s[44:45]
	v_cndmask_b32_e64 v147, v5, v7, s[44:45]
	s_nop 1
	v_mov_b32_dpp v146, v145 quad_perm:[2,3,0,1] row_mask:0xf bank_mask:0xf
	v_mov_b32_dpp v156, v147 quad_perm:[2,3,0,1] row_mask:0xf bank_mask:0xf
	v_cndmask_b32_e64 v6, v6, v146, s[44:45]
	v_cndmask_b32_e64 v4, v146, v4, s[44:45]
	v_cndmask_b32_e64 v7, v7, v156, s[44:45]
	v_cndmask_b32_e64 v5, v156, v5, s[44:45]
	v_cndmask_b32_e64 v145, v8, v9, s[42:43]
	v_cndmask_b32_e64 v147, v10, v11, s[42:43]
	s_nop 1
	v_mov_b32_dpp v146, v145 quad_perm:[1,0,3,2] row_mask:0xf bank_mask:0xf
	v_mov_b32_dpp v156, v147 quad_perm:[1,0,3,2] row_mask:0xf bank_mask:0xf
	v_cndmask_b32_e64 v9, v9, v146, s[42:43]
	v_cndmask_b32_e64 v8, v146, v8, s[42:43]
	v_cndmask_b32_e64 v11, v11, v156, s[42:43]
	v_cndmask_b32_e64 v10, v156, v10, s[42:43]
	v_cndmask_b32_e64 v145, v8, v10, s[44:45]
	v_cndmask_b32_e64 v147, v9, v11, s[44:45]
	s_nop 1
	v_mov_b32_dpp v146, v145 quad_perm:[2,3,0,1] row_mask:0xf bank_mask:0xf
	v_mov_b32_dpp v156, v147 quad_perm:[2,3,0,1] row_mask:0xf bank_mask:0xf
	v_cndmask_b32_e64 v10, v10, v146, s[44:45]
	v_cndmask_b32_e64 v8, v146, v8, s[44:45]
	v_cndmask_b32_e64 v11, v11, v156, s[44:45]
	v_cndmask_b32_e64 v9, v156, v9, s[44:45]
	v_cndmask_b32_e64 v145, v12, v13, s[42:43]
	v_cndmask_b32_e64 v147, v14, v15, s[42:43]
	s_nop 1
	v_mov_b32_dpp v146, v145 quad_perm:[1,0,3,2] row_mask:0xf bank_mask:0xf
	v_mov_b32_dpp v156, v147 quad_perm:[1,0,3,2] row_mask:0xf bank_mask:0xf
	v_cndmask_b32_e64 v13, v13, v146, s[42:43]
	v_cndmask_b32_e64 v12, v146, v12, s[42:43]
	v_cndmask_b32_e64 v15, v15, v156, s[42:43]
	v_cndmask_b32_e64 v14, v156, v14, s[42:43]
	v_cndmask_b32_e64 v145, v12, v14, s[44:45]
	v_cndmask_b32_e64 v147, v13, v15, s[44:45]
	s_nop 1
	v_mov_b32_dpp v146, v145 quad_perm:[2,3,0,1] row_mask:0xf bank_mask:0xf
	v_mov_b32_dpp v156, v147 quad_perm:[2,3,0,1] row_mask:0xf bank_mask:0xf
	v_cndmask_b32_e64 v14, v14, v146, s[44:45]
	v_cndmask_b32_e64 v12, v146, v12, s[44:45]
	v_cndmask_b32_e64 v15, v15, v156, s[44:45]
	v_cndmask_b32_e64 v13, v156, v13, s[44:45]
	v_cndmask_b32_e64 v145, v16, v17, s[42:43]
	v_cndmask_b32_e64 v147, v18, v19, s[42:43]
	s_nop 1
	v_mov_b32_dpp v146, v145 quad_perm:[1,0,3,2] row_mask:0xf bank_mask:0xf
	v_mov_b32_dpp v156, v147 quad_perm:[1,0,3,2] row_mask:0xf bank_mask:0xf
	v_cndmask_b32_e64 v17, v17, v146, s[42:43]
	v_cndmask_b32_e64 v16, v146, v16, s[42:43]
	v_cndmask_b32_e64 v19, v19, v156, s[42:43]
	v_cndmask_b32_e64 v18, v156, v18, s[42:43]
	v_cndmask_b32_e64 v145, v16, v18, s[44:45]
	v_cndmask_b32_e64 v147, v17, v19, s[44:45]
	s_nop 1
	v_mov_b32_dpp v146, v145 quad_perm:[2,3,0,1] row_mask:0xf bank_mask:0xf
	v_mov_b32_dpp v156, v147 quad_perm:[2,3,0,1] row_mask:0xf bank_mask:0xf
	v_cndmask_b32_e64 v18, v18, v146, s[44:45]
	v_cndmask_b32_e64 v16, v146, v16, s[44:45]
	v_cndmask_b32_e64 v19, v19, v156, s[44:45]
	v_cndmask_b32_e64 v17, v156, v17, s[44:45]
	v_cndmask_b32_e64 v145, v20, v21, s[42:43]
	v_cndmask_b32_e64 v147, v22, v23, s[42:43]
	s_nop 1
	v_mov_b32_dpp v146, v145 quad_perm:[1,0,3,2] row_mask:0xf bank_mask:0xf
	v_mov_b32_dpp v156, v147 quad_perm:[1,0,3,2] row_mask:0xf bank_mask:0xf
	v_cndmask_b32_e64 v21, v21, v146, s[42:43]
	v_cndmask_b32_e64 v20, v146, v20, s[42:43]
	v_cndmask_b32_e64 v23, v23, v156, s[42:43]
	v_cndmask_b32_e64 v22, v156, v22, s[42:43]
	v_cndmask_b32_e64 v145, v20, v22, s[44:45]
	v_cndmask_b32_e64 v147, v21, v23, s[44:45]
	s_nop 1
	v_mov_b32_dpp v146, v145 quad_perm:[2,3,0,1] row_mask:0xf bank_mask:0xf
	v_mov_b32_dpp v156, v147 quad_perm:[2,3,0,1] row_mask:0xf bank_mask:0xf
	v_cndmask_b32_e64 v22, v22, v146, s[44:45]
	v_cndmask_b32_e64 v20, v146, v20, s[44:45]
	v_cndmask_b32_e64 v23, v23, v156, s[44:45]
	v_cndmask_b32_e64 v21, v156, v21, s[44:45]
	v_cndmask_b32_e64 v145, v24, v25, s[42:43]
	v_cndmask_b32_e64 v147, v26, v27, s[42:43]
	s_nop 1
	v_mov_b32_dpp v146, v145 quad_perm:[1,0,3,2] row_mask:0xf bank_mask:0xf
	v_mov_b32_dpp v156, v147 quad_perm:[1,0,3,2] row_mask:0xf bank_mask:0xf
	v_cndmask_b32_e64 v25, v25, v146, s[42:43]
	v_cndmask_b32_e64 v24, v146, v24, s[42:43]
	v_cndmask_b32_e64 v27, v27, v156, s[42:43]
	v_cndmask_b32_e64 v26, v156, v26, s[42:43]
	v_cndmask_b32_e64 v145, v24, v26, s[44:45]
	v_cndmask_b32_e64 v147, v25, v27, s[44:45]
	s_nop 1
	v_mov_b32_dpp v146, v145 quad_perm:[2,3,0,1] row_mask:0xf bank_mask:0xf
	v_mov_b32_dpp v156, v147 quad_perm:[2,3,0,1] row_mask:0xf bank_mask:0xf
	v_cndmask_b32_e64 v26, v26, v146, s[44:45]
	v_cndmask_b32_e64 v24, v146, v24, s[44:45]
	v_cndmask_b32_e64 v27, v27, v156, s[44:45]
	v_cndmask_b32_e64 v25, v156, v25, s[44:45]
	v_cndmask_b32_e64 v145, v28, v29, s[42:43]
	v_cndmask_b32_e64 v147, v30, v31, s[42:43]
	s_nop 1
	v_mov_b32_dpp v146, v145 quad_perm:[1,0,3,2] row_mask:0xf bank_mask:0xf
	v_mov_b32_dpp v156, v147 quad_perm:[1,0,3,2] row_mask:0xf bank_mask:0xf
	v_cndmask_b32_e64 v29, v29, v146, s[42:43]
	v_cndmask_b32_e64 v28, v146, v28, s[42:43]
	v_cndmask_b32_e64 v31, v31, v156, s[42:43]
	v_cndmask_b32_e64 v30, v156, v30, s[42:43]
	v_cndmask_b32_e64 v145, v28, v30, s[44:45]
	v_cndmask_b32_e64 v147, v29, v31, s[44:45]
	s_nop 1
	v_mov_b32_dpp v146, v145 quad_perm:[2,3,0,1] row_mask:0xf bank_mask:0xf
	v_mov_b32_dpp v156, v147 quad_perm:[2,3,0,1] row_mask:0xf bank_mask:0xf
; #define LAS __attribute__((address_space(3)))
; __device__ __forceinline__ unsigned pk2(float lo, float hi) { const f32x2_t_ v = {lo, hi}; return __builtin_bit_cast(unsigned, __builtin_convertvector(v, bf16x2_t_)); }
; __device__ __forceinline__ void hg_chunk(const LAS unsigned char* sl, f32x4 (&S)[8], float* Orow, int nvalid, int vs, int lane) {
;     const int r = lane & 15, q = lane >> 4;
;     const bf16x8 vfr = *(const LAS bf16x8*)(sl + 16384 + ((vs * 64 + lane) << 4));
;     f32x4 o0 = {0.f, 0.f, 0.f, 0.f}, o1 = {0.f, 0.f, 0.f, 0.f};
;     { const bf16x8 s0 = *(const LAS bf16x8*)(sl + 24576 + (lane << 4)), s1 = *(const LAS bf16x8*)(sl + 24576 + ((64 + lane) << 4));
;       o0 = __builtin_amdgcn_mfma_f32_16x16x32_bf16(s0, vfr, o0, 0, 0, 0); o1 = __builtin_amdgcn_mfma_f32_16x16x32_bf16(s1, vfr, o1, 0, 0, 0); }
; #pragma unroll
;     for (int m = 0; m < 4; ++m) {
;         v4u sw; sw.x = pk2(S[2 * m][0], S[2 * m][1]); sw.y = pk2(S[2 * m][2], S[2 * m][3]); sw.z = pk2(S[2 * m + 1][0], S[2 * m + 1][1]); sw.w = pk2(S[2 * m + 1][2], S[2 * m + 1][3]);
;         const bf16x8 sb = __builtin_bit_cast(bf16x8, sw);
;         const bf16x8 a0 = *(const LAS bf16x8*)(sl + ((m * 64 + lane) << 4)), a1 = *(const LAS bf16x8*)(sl + (((4 + m) * 64 + lane) << 4));
;         o0 = __builtin_amdgcn_mfma_f32_16x16x32_bf16(a0, sb, o0, 0, 0, 0); o1 = __builtin_amdgcn_mfma_f32_16x16x32_bf16(a1, sb, o1, 0, 0, 0);
;     }
; #pragma unroll
;     for (int i = 0; i < 4; ++i) { const int c0 = 4 * q + i;
;         if (c0 < nvalid) Orow[(size_t)c0 * DA + 16 * vs + r] = o0[i];
;         if (c0 + 16 < nvalid) Orow[(size_t)(c0 + 16) * DA + 16 * vs + r] = o1[i]; }
; #pragma unroll
;     for (int kb = 0; kb < 8; ++kb) { const f32x4 d = *(const LAS f32x4*)(sl + 26624 + ((16 * kb + 4 * q) << 2));
;         const bf16x8 ke = *(const LAS bf16x8*)(sl + 8192 + ((kb * 64 + lane) << 4));
;         S[kb] = __builtin_amdgcn_mfma_f32_16x16x32_bf16(ke, vfr, S[kb] * d, 0, 0, 0); }
; __device__ __forceinline__ void hg_seq(const Frame& F, unsigned char* ws, const float* s0, float* sout, float* Og, int seq, bool sample, int vs_base, int nvs) {
;     ...
;     if (sample && active) {
; #pragma unroll
;         for (int kb = 0; kb < 8; ++kb)
; #pragma unroll
;             for (int i = 0; i < 4; ++i) S[kb][i] = s0[((size_t)seq * 128 + 16 * kb + 4 * q + i) * 128 + 16 * vs + r];
;     } else {
	v_cndmask_b32_e64 v30, v30, v146, s[44:45]
	v_cndmask_b32_e64 v28, v146, v28, s[44:45]
	v_cndmask_b32_e64 v31, v31, v156, s[44:45]
	v_cndmask_b32_e64 v29, v156, v29, s[44:45]
	v_cndmask_b32_e64 v145, v32, v33, s[42:43]
	v_cndmask_b32_e64 v147, v34, v35, s[42:43]
	s_nop 1
	v_mov_b32_dpp v146, v145 quad_perm:[1,0,3,2] row_mask:0xf bank_mask:0xf
	v_mov_b32_dpp v156, v147 quad_perm:[1,0,3,2] row_mask:0xf bank_mask:0xf
	v_cndmask_b32_e64 v33, v33, v146, s[42:43]
	v_cndmask_b32_e64 v32, v146, v32, s[42:43]
	v_cndmask_b32_e64 v35, v35, v156, s[42:43]
	v_cndmask_b32_e64 v34, v156, v34, s[42:43]
	v_cndmask_b32_e64 v145, v32, v34, s[44:45]
	v_cndmask_b32_e64 v147, v33, v35, s[44:45]
	s_nop 1
	v_mov_b32_dpp v146, v145 quad_perm:[2,3,0,1] row_mask:0xf bank_mask:0xf
	v_mov_b32_dpp v156, v147 quad_perm:[2,3,0,1] row_mask:0xf bank_mask:0xf
	v_cndmask_b32_e64 v34, v34, v146, s[44:45]
	v_cndmask_b32_e64 v32, v146, v32, s[44:45]
	v_cndmask_b32_e64 v35, v35, v156, s[44:45]
	v_cndmask_b32_e64 v33, v156, v33, s[44:45]
	v_mov_b32_e32 v1, v142
	v_mov_b32_e32 v2, v143
	v_mov_b32_e32 v3, v144
	ds_read_b128 v[164:167], v3 offset:26624
	ds_read_b128 v[168:171], v3 offset:26688
	ds_read_b128 v[172:175], v3 offset:26752
	ds_read_b128 v[176:179], v3 offset:26816
	ds_read_b128 v[180:183], v3 offset:26880
	ds_read_b128 v[184:187], v3 offset:26944
	ds_read_b128 v[148:151], v3 offset:27008
	ds_read_b128 v[152:155], v3 offset:27072
	ds_read_b128 v[84:87], v2 offset:16384
	ds_read_b128 v[88:91], v1 offset:24576
	ds_read_b128 v[92:95], v1 offset:0
	ds_read_b128 v[96:99], v1 offset:1024
	ds_read_b128 v[100:103], v1 offset:2048
	ds_read_b128 v[104:107], v1 offset:3072
	v_cvt_pk_bf16_f32 v68, v4, v5
	v_cvt_pk_bf16_f32 v69, v6, v7
	v_cvt_pk_bf16_f32 v70, v8, v9
	v_cvt_pk_bf16_f32 v71, v10, v11
	v_cvt_pk_bf16_f32 v72, v12, v13
	v_cvt_pk_bf16_f32 v73, v14, v15
	v_cvt_pk_bf16_f32 v74, v16, v17
	v_cvt_pk_bf16_f32 v75, v18, v19
	v_cvt_pk_bf16_f32 v76, v20, v21
	v_cvt_pk_bf16_f32 v77, v22, v23
	v_cvt_pk_bf16_f32 v78, v24, v25
	v_cvt_pk_bf16_f32 v79, v26, v27
	v_cvt_pk_bf16_f32 v80, v28, v29
	v_cvt_pk_bf16_f32 v81, v30, v31
	v_cvt_pk_bf16_f32 v82, v32, v33
	v_cvt_pk_bf16_f32 v83, v34, v35
	s_waitcnt lgkmcnt(6)
	v_pk_mul_f32 v[4:5], v[4:5], v[164:165]
	v_pk_mul_f32 v[6:7], v[6:7], v[166:167]
	v_pk_mul_f32 v[8:9], v[8:9], v[168:169]
	v_pk_mul_f32 v[10:11], v[10:11], v[170:171]
	v_pk_mul_f32 v[12:13], v[12:13], v[172:173]
	v_pk_mul_f32 v[14:15], v[14:15], v[174:175]
	v_pk_mul_f32 v[16:17], v[16:17], v[176:177]
	v_pk_mul_f32 v[18:19], v[18:19], v[178:179]
	v_pk_mul_f32 v[20:21], v[20:21], v[180:181]
	v_pk_mul_f32 v[22:23], v[22:23], v[182:183]
	v_pk_mul_f32 v[24:25], v[24:25], v[184:185]
	v_pk_mul_f32 v[26:27], v[26:27], v[186:187]
	v_pk_mul_f32 v[28:29], v[28:29], v[148:149]
	v_pk_mul_f32 v[30:31], v[30:31], v[150:151]
	v_pk_mul_f32 v[32:33], v[32:33], v[152:153]
	v_pk_mul_f32 v[34:35], v[34:35], v[154:155]
	ds_read_b128 v[108:111], v1 offset:8192
	ds_read_b128 v[112:115], v1 offset:9216
	ds_read_b128 v[116:119], v1 offset:10240
	ds_read_b128 v[120:123], v1 offset:11264
	ds_read_b128 v[124:127], v1 offset:12288
	ds_read_b128 v[128:131], v1 offset:13312
	ds_read_b128 v[132:135], v1 offset:14336
	ds_read_b128 v[136:139], v1 offset:15360
	s_waitcnt lgkmcnt(12)
	v_mfma_f32_16x16x32_bf16 v[196:199], v[88:91], v[84:87], 0
	s_waitcnt lgkmcnt(11)
	v_mfma_f32_16x16x32_bf16 v[196:199], v[92:95], v[68:71], v[196:199]
	s_waitcnt lgkmcnt(10)
	v_mfma_f32_16x16x32_bf16 v[196:199], v[96:99], v[72:75], v[196:199]
	s_waitcnt lgkmcnt(9)
	v_mfma_f32_16x16x32_bf16 v[196:199], v[100:103], v[76:79], v[196:199]
	s_waitcnt lgkmcnt(8)
	v_mfma_f32_16x16x32_bf16 v[196:199], v[104:107], v[80:83], v[196:199]
	s_waitcnt lgkmcnt(7)
	v_mfma_f32_16x16x32_bf16 v[4:7], v[108:111], v[84:87], v[4:7]
	s_waitcnt lgkmcnt(6)
	v_mfma_f32_16x16x32_bf16 v[8:11], v[112:115], v[84:87], v[8:11]
	s_waitcnt lgkmcnt(5)
	v_mfma_f32_16x16x32_bf16 v[12:15], v[116:119], v[84:87], v[12:15]
	s_waitcnt lgkmcnt(4)
	v_mfma_f32_16x16x32_bf16 v[16:19], v[120:123], v[84:87], v[16:19]
	s_waitcnt lgkmcnt(3)
	v_mfma_f32_16x16x32_bf16 v[20:23], v[124:127], v[84:87], v[20:23]
	s_waitcnt lgkmcnt(2)
	v_mfma_f32_16x16x32_bf16 v[24:27], v[128:131], v[84:87], v[24:27]
	s_waitcnt lgkmcnt(1)
	v_mfma_f32_16x16x32_bf16 v[28:31], v[132:135], v[84:87], v[28:31]
	s_waitcnt lgkmcnt(0)
; #define LAS __attribute__((address_space(3)))
; __device__ __forceinline__ void hg_chunk(const LAS unsigned char* sl, f32x4 (&S)[8], float* Orow, int nvalid, int vs, int lane) {
;     ...
;     for (int i = 0; i < 4; ++i) { const int c0 = 4 * q + i;
;         if (c0 < nvalid) Orow[(size_t)c0 * DA + 16 * vs + r] = o0[i];
;         if (c0 + 16 < nvalid) Orow[(size_t)(c0 + 16) * DA + 16 * vs + r] = o1[i]; }
; #pragma unroll
;     for (int kb = 0; kb < 8; ++kb) { const f32x4 d = *(const LAS f32x4*)(sl + 26624 + ((16 * kb + 4 * q) << 2));
;         const bf16x8 ke = *(const LAS bf16x8*)(sl + 8192 + ((kb * 64 + lane) << 4));
;         S[kb] = __builtin_amdgcn_mfma_f32_16x16x32_bf16(ke, vfr, S[kb] * d, 0, 0, 0); }
; __device__ __forceinline__ void hg_seq(const Frame& F, unsigned char* ws, const float* s0, float* sout, float* Og, int seq, bool sample, int vs_base, int nvs) {
;     ...
;     if (active) {
; #pragma unroll
;     for (int kb = 0; kb < 8; ++kb)
; #pragma unroll
;         for (int i = 0; i < 4; ++i) sout[((size_t)seq * 128 + 16 * kb + 4 * q + i) * 128 + 16 * vs + r] = S[kb][i];
;     }
	v_mfma_f32_16x16x32_bf16 v[32:35], v[136:139], v[84:87], v[32:35]
	s_mov_b32 exec_hi, 0
	global_store_dword v208, v196, s[12:13]
	global_store_dword v208, v197, s[12:13] offset:2048
	global_store_dword v209, v198, s[12:13]
	global_store_dword v209, v199, s[12:13] offset:2048
	s_mov_b64 exec, -1
	s_add_u32 s12, s12, 0x80000
	s_addc_u32 s13, s13, 0
	s_nop 7
	v_cndmask_b32_e64 v145, v4, v5, s[42:43]
	v_cndmask_b32_e64 v147, v6, v7, s[42:43]
	s_nop 1
	v_mov_b32_dpp v146, v145 quad_perm:[1,0,3,2] row_mask:0xf bank_mask:0xf
	v_mov_b32_dpp v156, v147 quad_perm:[1,0,3,2] row_mask:0xf bank_mask:0xf
	v_cndmask_b32_e64 v5, v5, v146, s[42:43]
	v_cndmask_b32_e64 v4, v146, v4, s[42:43]
	v_cndmask_b32_e64 v7, v7, v156, s[42:43]
	v_cndmask_b32_e64 v6, v156, v6, s[42:43]
	v_cndmask_b32_e64 v145, v4, v6, s[44:45]
	v_cndmask_b32_e64 v147, v5, v7, s[44:45]
	s_nop 1
	v_mov_b32_dpp v146, v145 quad_perm:[2,3,0,1] row_mask:0xf bank_mask:0xf
	v_mov_b32_dpp v156, v147 quad_perm:[2,3,0,1] row_mask:0xf bank_mask:0xf
	v_cndmask_b32_e64 v6, v6, v146, s[44:45]
	v_cndmask_b32_e64 v4, v146, v4, s[44:45]
	v_cndmask_b32_e64 v7, v7, v156, s[44:45]
	v_cndmask_b32_e64 v5, v156, v5, s[44:45]
	v_cndmask_b32_e64 v145, v8, v9, s[42:43]
	v_cndmask_b32_e64 v147, v10, v11, s[42:43]
	s_nop 1
	v_mov_b32_dpp v146, v145 quad_perm:[1,0,3,2] row_mask:0xf bank_mask:0xf
	v_mov_b32_dpp v156, v147 quad_perm:[1,0,3,2] row_mask:0xf bank_mask:0xf
	v_cndmask_b32_e64 v9, v9, v146, s[42:43]
	v_cndmask_b32_e64 v8, v146, v8, s[42:43]
	v_cndmask_b32_e64 v11, v11, v156, s[42:43]
	v_cndmask_b32_e64 v10, v156, v10, s[42:43]
	v_cndmask_b32_e64 v145, v8, v10, s[44:45]
	v_cndmask_b32_e64 v147, v9, v11, s[44:45]
	s_nop 1
	v_mov_b32_dpp v146, v145 quad_perm:[2,3,0,1] row_mask:0xf bank_mask:0xf
	v_mov_b32_dpp v156, v147 quad_perm:[2,3,0,1] row_mask:0xf bank_mask:0xf
	v_cndmask_b32_e64 v10, v10, v146, s[44:45]
	v_cndmask_b32_e64 v8, v146, v8, s[44:45]
	v_cndmask_b32_e64 v11, v11, v156, s[44:45]
	v_cndmask_b32_e64 v9, v156, v9, s[44:45]
	v_cndmask_b32_e64 v145, v12, v13, s[42:43]
	v_cndmask_b32_e64 v147, v14, v15, s[42:43]
	s_nop 1
	v_mov_b32_dpp v146, v145 quad_perm:[1,0,3,2] row_mask:0xf bank_mask:0xf
	v_mov_b32_dpp v156, v147 quad_perm:[1,0,3,2] row_mask:0xf bank_mask:0xf
	v_cndmask_b32_e64 v13, v13, v146, s[42:43]
	v_cndmask_b32_e64 v12, v146, v12, s[42:43]
	v_cndmask_b32_e64 v15, v15, v156, s[42:43]
	v_cndmask_b32_e64 v14, v156, v14, s[42:43]
	v_cndmask_b32_e64 v145, v12, v14, s[44:45]
	v_cndmask_b32_e64 v147, v13, v15, s[44:45]
	s_nop 1
	v_mov_b32_dpp v146, v145 quad_perm:[2,3,0,1] row_mask:0xf bank_mask:0xf
	v_mov_b32_dpp v156, v147 quad_perm:[2,3,0,1] row_mask:0xf bank_mask:0xf
	v_cndmask_b32_e64 v14, v14, v146, s[44:45]
	v_cndmask_b32_e64 v12, v146, v12, s[44:45]
	v_cndmask_b32_e64 v15, v15, v156, s[44:45]
	v_cndmask_b32_e64 v13, v156, v13, s[44:45]
	v_cndmask_b32_e64 v145, v16, v17, s[42:43]
	v_cndmask_b32_e64 v147, v18, v19, s[42:43]
	s_nop 1
	v_mov_b32_dpp v146, v145 quad_perm:[1,0,3,2] row_mask:0xf bank_mask:0xf
	v_mov_b32_dpp v156, v147 quad_perm:[1,0,3,2] row_mask:0xf bank_mask:0xf
	v_cndmask_b32_e64 v17, v17, v146, s[42:43]
	v_cndmask_b32_e64 v16, v146, v16, s[42:43]
	v_cndmask_b32_e64 v19, v19, v156, s[42:43]
	v_cndmask_b32_e64 v18, v156, v18, s[42:43]
	v_cndmask_b32_e64 v145, v16, v18, s[44:45]
	v_cndmask_b32_e64 v147, v17, v19, s[44:45]
	s_nop 1
	v_mov_b32_dpp v146, v145 quad_perm:[2,3,0,1] row_mask:0xf bank_mask:0xf
	v_mov_b32_dpp v156, v147 quad_perm:[2,3,0,1] row_mask:0xf bank_mask:0xf
	v_cndmask_b32_e64 v18, v18, v146, s[44:45]
	v_cndmask_b32_e64 v16, v146, v16, s[44:45]
	v_cndmask_b32_e64 v19, v19, v156, s[44:45]
	v_cndmask_b32_e64 v17, v156, v17, s[44:45]
	v_cndmask_b32_e64 v145, v20, v21, s[42:43]
	v_cndmask_b32_e64 v147, v22, v23, s[42:43]
	s_nop 1
	v_mov_b32_dpp v146, v145 quad_perm:[1,0,3,2] row_mask:0xf bank_mask:0xf
	v_mov_b32_dpp v156, v147 quad_perm:[1,0,3,2] row_mask:0xf bank_mask:0xf
	v_cndmask_b32_e64 v21, v21, v146, s[42:43]
	v_cndmask_b32_e64 v20, v146, v20, s[42:43]
	v_cndmask_b32_e64 v23, v23, v156, s[42:43]
	v_cndmask_b32_e64 v22, v156, v22, s[42:43]
	v_cndmask_b32_e64 v145, v20, v22, s[44:45]
	v_cndmask_b32_e64 v147, v21, v23, s[44:45]
	s_nop 1
	v_mov_b32_dpp v146, v145 quad_perm:[2,3,0,1] row_mask:0xf bank_mask:0xf
	v_mov_b32_dpp v156, v147 quad_perm:[2,3,0,1] row_mask:0xf bank_mask:0xf
	v_cndmask_b32_e64 v22, v22, v146, s[44:45]
	v_cndmask_b32_e64 v20, v146, v20, s[44:45]
	v_cndmask_b32_e64 v23, v23, v156, s[44:45]
	v_cndmask_b32_e64 v21, v156, v21, s[44:45]
	v_cndmask_b32_e64 v145, v24, v25, s[42:43]
	v_cndmask_b32_e64 v147, v26, v27, s[42:43]
	s_nop 1
	v_mov_b32_dpp v146, v145 quad_perm:[1,0,3,2] row_mask:0xf bank_mask:0xf
	v_mov_b32_dpp v156, v147 quad_perm:[1,0,3,2] row_mask:0xf bank_mask:0xf
	v_cndmask_b32_e64 v25, v25, v146, s[42:43]
	v_cndmask_b32_e64 v24, v146, v24, s[42:43]
	v_cndmask_b32_e64 v27, v27, v156, s[42:43]
	v_cndmask_b32_e64 v26, v156, v26, s[42:43]
	v_cndmask_b32_e64 v145, v24, v26, s[44:45]
	v_cndmask_b32_e64 v147, v25, v27, s[44:45]
	s_nop 1
	v_mov_b32_dpp v146, v145 quad_perm:[2,3,0,1] row_mask:0xf bank_mask:0xf
	v_mov_b32_dpp v156, v147 quad_perm:[2,3,0,1] row_mask:0xf bank_mask:0xf
	v_cndmask_b32_e64 v26, v26, v146, s[44:45]
	v_cndmask_b32_e64 v24, v146, v24, s[44:45]
	v_cndmask_b32_e64 v27, v27, v156, s[44:45]
	v_cndmask_b32_e64 v25, v156, v25, s[44:45]
	v_cndmask_b32_e64 v145, v28, v29, s[42:43]
	v_cndmask_b32_e64 v147, v30, v31, s[42:43]
	s_nop 1
	v_mov_b32_dpp v146, v145 quad_perm:[1,0,3,2] row_mask:0xf bank_mask:0xf
	v_mov_b32_dpp v156, v147 quad_perm:[1,0,3,2] row_mask:0xf bank_mask:0xf
	v_cndmask_b32_e64 v29, v29, v146, s[42:43]
; __device__ __forceinline__ void hg_seq(const Frame& F, unsigned char* ws, const float* s0, float* sout, float* Og, int seq, bool sample, int vs_base, int nvs) {
;     ...
;     if (sample && active) {
; #pragma unroll
;         for (int kb = 0; kb < 8; ++kb)
; #pragma unroll
;             for (int i = 0; i < 4; ++i) S[kb][i] = s0[((size_t)seq * 128 + 16 * kb + 4 * q + i) * 128 + 16 * vs + r];
;     } else {
;     ...
;     if (active) {
; #pragma unroll
;     for (int kb = 0; kb < 8; ++kb)
; #pragma unroll
;         for (int i = 0; i < 4; ++i) sout[((size_t)seq * 128 + 16 * kb + 4 * q + i) * 128 + 16 * vs + r] = S[kb][i];
;     }
	v_cndmask_b32_e64 v28, v146, v28, s[42:43]
	v_cndmask_b32_e64 v31, v31, v156, s[42:43]
	v_cndmask_b32_e64 v30, v156, v30, s[42:43]
	v_cndmask_b32_e64 v145, v28, v30, s[44:45]
	v_cndmask_b32_e64 v147, v29, v31, s[44:45]
	s_nop 1
	v_mov_b32_dpp v146, v145 quad_perm:[2,3,0,1] row_mask:0xf bank_mask:0xf
	v_mov_b32_dpp v156, v147 quad_perm:[2,3,0,1] row_mask:0xf bank_mask:0xf
	v_cndmask_b32_e64 v30, v30, v146, s[44:45]
	v_cndmask_b32_e64 v28, v146, v28, s[44:45]
	v_cndmask_b32_e64 v31, v31, v156, s[44:45]
	v_cndmask_b32_e64 v29, v156, v29, s[44:45]
	v_cndmask_b32_e64 v145, v32, v33, s[42:43]
	v_cndmask_b32_e64 v147, v34, v35, s[42:43]
	s_nop 1
	v_mov_b32_dpp v146, v145 quad_perm:[1,0,3,2] row_mask:0xf bank_mask:0xf
	v_mov_b32_dpp v156, v147 quad_perm:[1,0,3,2] row_mask:0xf bank_mask:0xf
	v_cndmask_b32_e64 v33, v33, v146, s[42:43]
	v_cndmask_b32_e64 v32, v146, v32, s[42:43]
	v_cndmask_b32_e64 v35, v35, v156, s[42:43]
	v_cndmask_b32_e64 v34, v156, v34, s[42:43]
	v_cndmask_b32_e64 v145, v32, v34, s[44:45]
	v_cndmask_b32_e64 v147, v33, v35, s[44:45]
	s_nop 1
	v_mov_b32_dpp v146, v145 quad_perm:[2,3,0,1] row_mask:0xf bank_mask:0xf
	v_mov_b32_dpp v156, v147 quad_perm:[2,3,0,1] row_mask:0xf bank_mask:0xf
	v_cndmask_b32_e64 v34, v34, v146, s[44:45]
	v_cndmask_b32_e64 v32, v146, v32, s[44:45]
	v_cndmask_b32_e64 v35, v35, v156, s[44:45]
	v_cndmask_b32_e64 v33, v156, v33, s[44:45]
	global_store_dwordx4 v200, v[4:7], s[10:11]
	global_store_dwordx4 v201, v[8:11], s[10:11]
	global_store_dwordx4 v202, v[12:15], s[10:11]
	global_store_dwordx4 v203, v[16:19], s[10:11]
	global_store_dwordx4 v204, v[20:23], s[10:11]
	global_store_dwordx4 v205, v[24:27], s[10:11]
	global_store_dwordx4 v206, v[28:31], s[10:11]
	global_store_dwordx4 v207, v[32:35], s[10:11]
	s_add_u32 s10, s10, s34
	s_addc_u32 s11, s11, 0
	s_waitcnt vmcnt(12)
	global_load_dwordx4 v[4:7], v200, s[8:9]
	global_load_dwordx4 v[8:11], v201, s[8:9]
	global_load_dwordx4 v[12:15], v202, s[8:9]
	global_load_dwordx4 v[16:19], v203, s[8:9]
	global_load_dwordx4 v[20:23], v204, s[8:9]
	global_load_dwordx4 v[24:27], v205, s[8:9]
	global_load_dwordx4 v[28:31], v206, s[8:9]
	global_load_dwordx4 v[32:35], v207, s[8:9]
	s_add_u32 s8, s8, s34
	s_addc_u32 s9, s9, 0
	v_cndmask_b32_e64 v145, v36, v37, s[42:43]
	v_cndmask_b32_e64 v147, v38, v39, s[42:43]
	s_nop 1
	v_mov_b32_dpp v146, v145 quad_perm:[1,0,3,2] row_mask:0xf bank_mask:0xf
	v_mov_b32_dpp v156, v147 quad_perm:[1,0,3,2] row_mask:0xf bank_mask:0xf
	v_cndmask_b32_e64 v37, v37, v146, s[42:43]
	v_cndmask_b32_e64 v36, v146, v36, s[42:43]
	v_cndmask_b32_e64 v39, v39, v156, s[42:43]
	v_cndmask_b32_e64 v38, v156, v38, s[42:43]
	v_cndmask_b32_e64 v145, v36, v38, s[44:45]
	v_cndmask_b32_e64 v147, v37, v39, s[44:45]
	s_nop 1
	v_mov_b32_dpp v146, v145 quad_perm:[2,3,0,1] row_mask:0xf bank_mask:0xf
	v_mov_b32_dpp v156, v147 quad_perm:[2,3,0,1] row_mask:0xf bank_mask:0xf
	v_cndmask_b32_e64 v38, v38, v146, s[44:45]
	v_cndmask_b32_e64 v36, v146, v36, s[44:45]
	v_cndmask_b32_e64 v39, v39, v156, s[44:45]
	v_cndmask_b32_e64 v37, v156, v37, s[44:45]
	v_cndmask_b32_e64 v145, v40, v41, s[42:43]
	v_cndmask_b32_e64 v147, v42, v43, s[42:43]
	s_nop 1
	v_mov_b32_dpp v146, v145 quad_perm:[1,0,3,2] row_mask:0xf bank_mask:0xf
	v_mov_b32_dpp v156, v147 quad_perm:[1,0,3,2] row_mask:0xf bank_mask:0xf
	v_cndmask_b32_e64 v41, v41, v146, s[42:43]
	v_cndmask_b32_e64 v40, v146, v40, s[42:43]
	v_cndmask_b32_e64 v43, v43, v156, s[42:43]
	v_cndmask_b32_e64 v42, v156, v42, s[42:43]
	v_cndmask_b32_e64 v145, v40, v42, s[44:45]
	v_cndmask_b32_e64 v147, v41, v43, s[44:45]
	s_nop 1
	v_mov_b32_dpp v146, v145 quad_perm:[2,3,0,1] row_mask:0xf bank_mask:0xf
	v_mov_b32_dpp v156, v147 quad_perm:[2,3,0,1] row_mask:0xf bank_mask:0xf
	v_cndmask_b32_e64 v42, v42, v146, s[44:45]
	v_cndmask_b32_e64 v40, v146, v40, s[44:45]
	v_cndmask_b32_e64 v43, v43, v156, s[44:45]
	v_cndmask_b32_e64 v41, v156, v41, s[44:45]
	v_cndmask_b32_e64 v145, v44, v45, s[42:43]
	v_cndmask_b32_e64 v147, v46, v47, s[42:43]
	s_nop 1
	v_mov_b32_dpp v146, v145 quad_perm:[1,0,3,2] row_mask:0xf bank_mask:0xf
	v_mov_b32_dpp v156, v147 quad_perm:[1,0,3,2] row_mask:0xf bank_mask:0xf
	v_cndmask_b32_e64 v45, v45, v146, s[42:43]
	v_cndmask_b32_e64 v44, v146, v44, s[42:43]
	v_cndmask_b32_e64 v47, v47, v156, s[42:43]
	v_cndmask_b32_e64 v46, v156, v46, s[42:43]
	v_cndmask_b32_e64 v145, v44, v46, s[44:45]
	v_cndmask_b32_e64 v147, v45, v47, s[44:45]
	s_nop 1
	v_mov_b32_dpp v146, v145 quad_perm:[2,3,0,1] row_mask:0xf bank_mask:0xf
	v_mov_b32_dpp v156, v147 quad_perm:[2,3,0,1] row_mask:0xf bank_mask:0xf
	v_cndmask_b32_e64 v46, v46, v146, s[44:45]
	v_cndmask_b32_e64 v44, v146, v44, s[44:45]
	v_cndmask_b32_e64 v47, v47, v156, s[44:45]
	v_cndmask_b32_e64 v45, v156, v45, s[44:45]
	v_cndmask_b32_e64 v145, v48, v49, s[42:43]
	v_cndmask_b32_e64 v147, v50, v51, s[42:43]
	s_nop 1
	v_mov_b32_dpp v146, v145 quad_perm:[1,0,3,2] row_mask:0xf bank_mask:0xf
	v_mov_b32_dpp v156, v147 quad_perm:[1,0,3,2] row_mask:0xf bank_mask:0xf
	v_cndmask_b32_e64 v49, v49, v146, s[42:43]
	v_cndmask_b32_e64 v48, v146, v48, s[42:43]
	v_cndmask_b32_e64 v51, v51, v156, s[42:43]
	v_cndmask_b32_e64 v50, v156, v50, s[42:43]
	v_cndmask_b32_e64 v145, v48, v50, s[44:45]
	v_cndmask_b32_e64 v147, v49, v51, s[44:45]
	s_nop 1
	v_mov_b32_dpp v146, v145 quad_perm:[2,3,0,1] row_mask:0xf bank_mask:0xf
	v_mov_b32_dpp v156, v147 quad_perm:[2,3,0,1] row_mask:0xf bank_mask:0xf
	v_cndmask_b32_e64 v50, v50, v146, s[44:45]
	v_cndmask_b32_e64 v48, v146, v48, s[44:45]
	v_cndmask_b32_e64 v51, v51, v156, s[44:45]
	v_cndmask_b32_e64 v49, v156, v49, s[44:45]
	v_cndmask_b32_e64 v145, v52, v53, s[42:43]
; #define LAS __attribute__((address_space(3)))
; __device__ __forceinline__ unsigned pk2(float lo, float hi) { const f32x2_t_ v = {lo, hi}; return __builtin_bit_cast(unsigned, __builtin_convertvector(v, bf16x2_t_)); }
; __device__ __forceinline__ void hg_chunk(const LAS unsigned char* sl, f32x4 (&S)[8], float* Orow, int nvalid, int vs, int lane) {
;     const int r = lane & 15, q = lane >> 4;
;     const bf16x8 vfr = *(const LAS bf16x8*)(sl + 16384 + ((vs * 64 + lane) << 4));
;     f32x4 o0 = {0.f, 0.f, 0.f, 0.f}, o1 = {0.f, 0.f, 0.f, 0.f};
;     { const bf16x8 s0 = *(const LAS bf16x8*)(sl + 24576 + (lane << 4)), s1 = *(const LAS bf16x8*)(sl + 24576 + ((64 + lane) << 4));
;       o0 = __builtin_amdgcn_mfma_f32_16x16x32_bf16(s0, vfr, o0, 0, 0, 0); o1 = __builtin_amdgcn_mfma_f32_16x16x32_bf16(s1, vfr, o1, 0, 0, 0); }
; #pragma unroll
;     for (int m = 0; m < 4; ++m) {
;         v4u sw; sw.x = pk2(S[2 * m][0], S[2 * m][1]); sw.y = pk2(S[2 * m][2], S[2 * m][3]); sw.z = pk2(S[2 * m + 1][0], S[2 * m + 1][1]); sw.w = pk2(S[2 * m + 1][2], S[2 * m + 1][3]);
;         const bf16x8 sb = __builtin_bit_cast(bf16x8, sw);
;         const bf16x8 a0 = *(const LAS bf16x8*)(sl + ((m * 64 + lane) << 4)), a1 = *(const LAS bf16x8*)(sl + (((4 + m) * 64 + lane) << 4));
;         o0 = __builtin_amdgcn_mfma_f32_16x16x32_bf16(a0, sb, o0, 0, 0, 0); o1 = __builtin_amdgcn_mfma_f32_16x16x32_bf16(a1, sb, o1, 0, 0, 0);
;     }
; #pragma unroll
;     for (int i = 0; i < 4; ++i) { const int c0 = 4 * q + i;
;         if (c0 < nvalid) Orow[(size_t)c0 * DA + 16 * vs + r] = o0[i];
;         if (c0 + 16 < nvalid) Orow[(size_t)(c0 + 16) * DA + 16 * vs + r] = o1[i]; }
; #pragma unroll
;     for (int kb = 0; kb < 8; ++kb) { const f32x4 d = *(const LAS f32x4*)(sl + 26624 + ((16 * kb + 4 * q) << 2));
;         const bf16x8 ke = *(const LAS bf16x8*)(sl + 8192 + ((kb * 64 + lane) << 4));
;         S[kb] = __builtin_amdgcn_mfma_f32_16x16x32_bf16(ke, vfr, S[kb] * d, 0, 0, 0); }
; __device__ __forceinline__ void hg_seq(const Frame& F, unsigned char* ws, const float* s0, float* sout, float* Og, int seq, bool sample, int vs_base, int nvs) {
;     ...
;     if (sample && active) {
; #pragma unroll
;         for (int kb = 0; kb < 8; ++kb)
; #pragma unroll
;             for (int i = 0; i < 4; ++i) S[kb][i] = s0[((size_t)seq * 128 + 16 * kb + 4 * q + i) * 128 + 16 * vs + r];
;     } else {
	v_cndmask_b32_e64 v147, v54, v55, s[42:43]
	s_nop 1
	v_mov_b32_dpp v146, v145 quad_perm:[1,0,3,2] row_mask:0xf bank_mask:0xf
	v_mov_b32_dpp v156, v147 quad_perm:[1,0,3,2] row_mask:0xf bank_mask:0xf
	v_cndmask_b32_e64 v53, v53, v146, s[42:43]
	v_cndmask_b32_e64 v52, v146, v52, s[42:43]
	v_cndmask_b32_e64 v55, v55, v156, s[42:43]
	v_cndmask_b32_e64 v54, v156, v54, s[42:43]
	v_cndmask_b32_e64 v145, v52, v54, s[44:45]
	v_cndmask_b32_e64 v147, v53, v55, s[44:45]
	s_nop 1
	v_mov_b32_dpp v146, v145 quad_perm:[2,3,0,1] row_mask:0xf bank_mask:0xf
	v_mov_b32_dpp v156, v147 quad_perm:[2,3,0,1] row_mask:0xf bank_mask:0xf
	v_cndmask_b32_e64 v54, v54, v146, s[44:45]
	v_cndmask_b32_e64 v52, v146, v52, s[44:45]
	v_cndmask_b32_e64 v55, v55, v156, s[44:45]
	v_cndmask_b32_e64 v53, v156, v53, s[44:45]
	v_cndmask_b32_e64 v145, v56, v57, s[42:43]
	v_cndmask_b32_e64 v147, v58, v59, s[42:43]
	s_nop 1
	v_mov_b32_dpp v146, v145 quad_perm:[1,0,3,2] row_mask:0xf bank_mask:0xf
	v_mov_b32_dpp v156, v147 quad_perm:[1,0,3,2] row_mask:0xf bank_mask:0xf
	v_cndmask_b32_e64 v57, v57, v146, s[42:43]
	v_cndmask_b32_e64 v56, v146, v56, s[42:43]
	v_cndmask_b32_e64 v59, v59, v156, s[42:43]
	v_cndmask_b32_e64 v58, v156, v58, s[42:43]
	v_cndmask_b32_e64 v145, v56, v58, s[44:45]
	v_cndmask_b32_e64 v147, v57, v59, s[44:45]
	s_nop 1
	v_mov_b32_dpp v146, v145 quad_perm:[2,3,0,1] row_mask:0xf bank_mask:0xf
	v_mov_b32_dpp v156, v147 quad_perm:[2,3,0,1] row_mask:0xf bank_mask:0xf
	v_cndmask_b32_e64 v58, v58, v146, s[44:45]
	v_cndmask_b32_e64 v56, v146, v56, s[44:45]
	v_cndmask_b32_e64 v59, v59, v156, s[44:45]
	v_cndmask_b32_e64 v57, v156, v57, s[44:45]
	v_cndmask_b32_e64 v145, v60, v61, s[42:43]
	v_cndmask_b32_e64 v147, v62, v63, s[42:43]
	s_nop 1
	v_mov_b32_dpp v146, v145 quad_perm:[1,0,3,2] row_mask:0xf bank_mask:0xf
	v_mov_b32_dpp v156, v147 quad_perm:[1,0,3,2] row_mask:0xf bank_mask:0xf
	v_cndmask_b32_e64 v61, v61, v146, s[42:43]
	v_cndmask_b32_e64 v60, v146, v60, s[42:43]
	v_cndmask_b32_e64 v63, v63, v156, s[42:43]
	v_cndmask_b32_e64 v62, v156, v62, s[42:43]
	v_cndmask_b32_e64 v145, v60, v62, s[44:45]
	v_cndmask_b32_e64 v147, v61, v63, s[44:45]
	s_nop 1
	v_mov_b32_dpp v146, v145 quad_perm:[2,3,0,1] row_mask:0xf bank_mask:0xf
	v_mov_b32_dpp v156, v147 quad_perm:[2,3,0,1] row_mask:0xf bank_mask:0xf
	v_cndmask_b32_e64 v62, v62, v146, s[44:45]
	v_cndmask_b32_e64 v60, v146, v60, s[44:45]
	v_cndmask_b32_e64 v63, v63, v156, s[44:45]
	v_cndmask_b32_e64 v61, v156, v61, s[44:45]
	v_cndmask_b32_e64 v145, v64, v65, s[42:43]
	v_cndmask_b32_e64 v147, v66, v67, s[42:43]
	s_nop 1
	v_mov_b32_dpp v146, v145 quad_perm:[1,0,3,2] row_mask:0xf bank_mask:0xf
	v_mov_b32_dpp v156, v147 quad_perm:[1,0,3,2] row_mask:0xf bank_mask:0xf
	v_cndmask_b32_e64 v65, v65, v146, s[42:43]
	v_cndmask_b32_e64 v64, v146, v64, s[42:43]
	v_cndmask_b32_e64 v67, v67, v156, s[42:43]
	v_cndmask_b32_e64 v66, v156, v66, s[42:43]
	v_cndmask_b32_e64 v145, v64, v66, s[44:45]
	v_cndmask_b32_e64 v147, v65, v67, s[44:45]
	s_nop 1
	v_mov_b32_dpp v146, v145 quad_perm:[2,3,0,1] row_mask:0xf bank_mask:0xf
	v_mov_b32_dpp v156, v147 quad_perm:[2,3,0,1] row_mask:0xf bank_mask:0xf
	v_cndmask_b32_e64 v66, v66, v146, s[44:45]
	v_cndmask_b32_e64 v64, v146, v64, s[44:45]
	v_cndmask_b32_e64 v67, v67, v156, s[44:45]
	v_cndmask_b32_e64 v65, v156, v65, s[44:45]
	v_add_u32_e32 v1, 0x6c00, v142
	v_add_u32_e32 v2, 0x6c00, v143
	v_add_u32_e32 v3, 0x6c00, v144
	ds_read_b128 v[164:167], v3 offset:26624
	ds_read_b128 v[168:171], v3 offset:26688
	ds_read_b128 v[172:175], v3 offset:26752
	ds_read_b128 v[176:179], v3 offset:26816
	ds_read_b128 v[180:183], v3 offset:26880
	ds_read_b128 v[184:187], v3 offset:26944
	ds_read_b128 v[148:151], v3 offset:27008
	ds_read_b128 v[152:155], v3 offset:27072
	ds_read_b128 v[84:87], v2 offset:16384
	ds_read_b128 v[88:91], v1 offset:24576
	ds_read_b128 v[92:95], v1 offset:0
	ds_read_b128 v[96:99], v1 offset:1024
	ds_read_b128 v[100:103], v1 offset:2048
	ds_read_b128 v[104:107], v1 offset:3072
	v_cvt_pk_bf16_f32 v68, v36, v37
	v_cvt_pk_bf16_f32 v69, v38, v39
	v_cvt_pk_bf16_f32 v70, v40, v41
	v_cvt_pk_bf16_f32 v71, v42, v43
	v_cvt_pk_bf16_f32 v72, v44, v45
	v_cvt_pk_bf16_f32 v73, v46, v47
	v_cvt_pk_bf16_f32 v74, v48, v49
	v_cvt_pk_bf16_f32 v75, v50, v51
	v_cvt_pk_bf16_f32 v76, v52, v53
	v_cvt_pk_bf16_f32 v77, v54, v55
	v_cvt_pk_bf16_f32 v78, v56, v57
	v_cvt_pk_bf16_f32 v79, v58, v59
	v_cvt_pk_bf16_f32 v80, v60, v61
	v_cvt_pk_bf16_f32 v81, v62, v63
	v_cvt_pk_bf16_f32 v82, v64, v65
	v_cvt_pk_bf16_f32 v83, v66, v67
	s_waitcnt lgkmcnt(6)
	v_pk_mul_f32 v[36:37], v[36:37], v[164:165]
	v_pk_mul_f32 v[38:39], v[38:39], v[166:167]
	v_pk_mul_f32 v[40:41], v[40:41], v[168:169]
	v_pk_mul_f32 v[42:43], v[42:43], v[170:171]
	v_pk_mul_f32 v[44:45], v[44:45], v[172:173]
	v_pk_mul_f32 v[46:47], v[46:47], v[174:175]
	v_pk_mul_f32 v[48:49], v[48:49], v[176:177]
	v_pk_mul_f32 v[50:51], v[50:51], v[178:179]
	v_pk_mul_f32 v[52:53], v[52:53], v[180:181]
	v_pk_mul_f32 v[54:55], v[54:55], v[182:183]
	v_pk_mul_f32 v[56:57], v[56:57], v[184:185]
	v_pk_mul_f32 v[58:59], v[58:59], v[186:187]
	v_pk_mul_f32 v[60:61], v[60:61], v[148:149]
	v_pk_mul_f32 v[62:63], v[62:63], v[150:151]
	v_pk_mul_f32 v[64:65], v[64:65], v[152:153]
	v_pk_mul_f32 v[66:67], v[66:67], v[154:155]
	ds_read_b128 v[108:111], v1 offset:8192
	ds_read_b128 v[112:115], v1 offset:9216
	ds_read_b128 v[116:119], v1 offset:10240
	ds_read_b128 v[120:123], v1 offset:11264
	ds_read_b128 v[124:127], v1 offset:12288
	ds_read_b128 v[128:131], v1 offset:13312
	ds_read_b128 v[132:135], v1 offset:14336
	ds_read_b128 v[136:139], v1 offset:15360
	s_waitcnt lgkmcnt(12)
; #define LAS __attribute__((address_space(3)))
; __device__ __forceinline__ unsigned pk2(float lo, float hi) { const f32x2_t_ v = {lo, hi}; return __builtin_bit_cast(unsigned, __builtin_convertvector(v, bf16x2_t_)); }
; __device__ __forceinline__ void hg_chunk(const LAS unsigned char* sl, f32x4 (&S)[8], float* Orow, int nvalid, int vs, int lane) {
;     ...
;     { const bf16x8 s0 = *(const LAS bf16x8*)(sl + 24576 + (lane << 4)), s1 = *(const LAS bf16x8*)(sl + 24576 + ((64 + lane) << 4));
;       o0 = __builtin_amdgcn_mfma_f32_16x16x32_bf16(s0, vfr, o0, 0, 0, 0); o1 = __builtin_amdgcn_mfma_f32_16x16x32_bf16(s1, vfr, o1, 0, 0, 0); }
; #pragma unroll
;     for (int m = 0; m < 4; ++m) {
;         v4u sw; sw.x = pk2(S[2 * m][0], S[2 * m][1]); sw.y = pk2(S[2 * m][2], S[2 * m][3]); sw.z = pk2(S[2 * m + 1][0], S[2 * m + 1][1]); sw.w = pk2(S[2 * m + 1][2], S[2 * m + 1][3]);
;         const bf16x8 sb = __builtin_bit_cast(bf16x8, sw);
;         const bf16x8 a0 = *(const LAS bf16x8*)(sl + ((m * 64 + lane) << 4)), a1 = *(const LAS bf16x8*)(sl + (((4 + m) * 64 + lane) << 4));
;         o0 = __builtin_amdgcn_mfma_f32_16x16x32_bf16(a0, sb, o0, 0, 0, 0); o1 = __builtin_amdgcn_mfma_f32_16x16x32_bf16(a1, sb, o1, 0, 0, 0);
;     }
; #pragma unroll
;     for (int i = 0; i < 4; ++i) { const int c0 = 4 * q + i;
;         if (c0 < nvalid) Orow[(size_t)c0 * DA + 16 * vs + r] = o0[i];
;         if (c0 + 16 < nvalid) Orow[(size_t)(c0 + 16) * DA + 16 * vs + r] = o1[i]; }
; #pragma unroll
;     for (int kb = 0; kb < 8; ++kb) { const f32x4 d = *(const LAS f32x4*)(sl + 26624 + ((16 * kb + 4 * q) << 2));
;         const bf16x8 ke = *(const LAS bf16x8*)(sl + 8192 + ((kb * 64 + lane) << 4));
;         S[kb] = __builtin_amdgcn_mfma_f32_16x16x32_bf16(ke, vfr, S[kb] * d, 0, 0, 0); }
; __device__ __forceinline__ void hg_seq(const Frame& F, unsigned char* ws, const float* s0, float* sout, float* Og, int seq, bool sample, int vs_base, int nvs) {
;     ...
;     if (active) {
; #pragma unroll
;     for (int kb = 0; kb < 8; ++kb)
; #pragma unroll
;         for (int i = 0; i < 4; ++i) sout[((size_t)seq * 128 + 16 * kb + 4 * q + i) * 128 + 16 * vs + r] = S[kb][i];
;     }
	v_mfma_f32_16x16x32_bf16 v[196:199], v[88:91], v[84:87], 0
	s_waitcnt lgkmcnt(11)
	v_mfma_f32_16x16x32_bf16 v[196:199], v[92:95], v[68:71], v[196:199]
	s_waitcnt lgkmcnt(10)
	v_mfma_f32_16x16x32_bf16 v[196:199], v[96:99], v[72:75], v[196:199]
	s_waitcnt lgkmcnt(9)
	v_mfma_f32_16x16x32_bf16 v[196:199], v[100:103], v[76:79], v[196:199]
	s_waitcnt lgkmcnt(8)
	v_mfma_f32_16x16x32_bf16 v[196:199], v[104:107], v[80:83], v[196:199]
	s_waitcnt lgkmcnt(7)
	v_mfma_f32_16x16x32_bf16 v[36:39], v[108:111], v[84:87], v[36:39]
	s_waitcnt lgkmcnt(6)
	v_mfma_f32_16x16x32_bf16 v[40:43], v[112:115], v[84:87], v[40:43]
	s_waitcnt lgkmcnt(5)
	v_mfma_f32_16x16x32_bf16 v[44:47], v[116:119], v[84:87], v[44:47]
	s_waitcnt lgkmcnt(4)
	v_mfma_f32_16x16x32_bf16 v[48:51], v[120:123], v[84:87], v[48:51]
	s_waitcnt lgkmcnt(3)
	v_mfma_f32_16x16x32_bf16 v[52:55], v[124:127], v[84:87], v[52:55]
	s_waitcnt lgkmcnt(2)
	v_mfma_f32_16x16x32_bf16 v[56:59], v[128:131], v[84:87], v[56:59]
	s_waitcnt lgkmcnt(1)
	v_mfma_f32_16x16x32_bf16 v[60:63], v[132:135], v[84:87], v[60:63]
	s_waitcnt lgkmcnt(0)
	v_mfma_f32_16x16x32_bf16 v[64:67], v[136:139], v[84:87], v[64:67]
	s_mov_b32 exec_hi, 0
	global_store_dword v208, v196, s[12:13]
	global_store_dword v208, v197, s[12:13] offset:2048
	global_store_dword v209, v198, s[12:13]
	global_store_dword v209, v199, s[12:13] offset:2048
	s_mov_b64 exec, -1
	s_add_u32 s12, s12, 0x80000
	s_addc_u32 s13, s13, 0
	s_nop 7
	v_cndmask_b32_e64 v145, v36, v37, s[42:43]
	v_cndmask_b32_e64 v147, v38, v39, s[42:43]
	s_nop 1
	v_mov_b32_dpp v146, v145 quad_perm:[1,0,3,2] row_mask:0xf bank_mask:0xf
	v_mov_b32_dpp v156, v147 quad_perm:[1,0,3,2] row_mask:0xf bank_mask:0xf
	v_cndmask_b32_e64 v37, v37, v146, s[42:43]
	v_cndmask_b32_e64 v36, v146, v36, s[42:43]
	v_cndmask_b32_e64 v39, v39, v156, s[42:43]
	v_cndmask_b32_e64 v38, v156, v38, s[42:43]
	v_cndmask_b32_e64 v145, v36, v38, s[44:45]
	v_cndmask_b32_e64 v147, v37, v39, s[44:45]
	s_nop 1
	v_mov_b32_dpp v146, v145 quad_perm:[2,3,0,1] row_mask:0xf bank_mask:0xf
	v_mov_b32_dpp v156, v147 quad_perm:[2,3,0,1] row_mask:0xf bank_mask:0xf
	v_cndmask_b32_e64 v38, v38, v146, s[44:45]
	v_cndmask_b32_e64 v36, v146, v36, s[44:45]
	v_cndmask_b32_e64 v39, v39, v156, s[44:45]
	v_cndmask_b32_e64 v37, v156, v37, s[44:45]
	v_cndmask_b32_e64 v145, v40, v41, s[42:43]
	v_cndmask_b32_e64 v147, v42, v43, s[42:43]
	s_nop 1
	v_mov_b32_dpp v146, v145 quad_perm:[1,0,3,2] row_mask:0xf bank_mask:0xf
	v_mov_b32_dpp v156, v147 quad_perm:[1,0,3,2] row_mask:0xf bank_mask:0xf
	v_cndmask_b32_e64 v41, v41, v146, s[42:43]
	v_cndmask_b32_e64 v40, v146, v40, s[42:43]
	v_cndmask_b32_e64 v43, v43, v156, s[42:43]
	v_cndmask_b32_e64 v42, v156, v42, s[42:43]
	v_cndmask_b32_e64 v145, v40, v42, s[44:45]
	v_cndmask_b32_e64 v147, v41, v43, s[44:45]
	s_nop 1
	v_mov_b32_dpp v146, v145 quad_perm:[2,3,0,1] row_mask:0xf bank_mask:0xf
	v_mov_b32_dpp v156, v147 quad_perm:[2,3,0,1] row_mask:0xf bank_mask:0xf
	v_cndmask_b32_e64 v42, v42, v146, s[44:45]
	v_cndmask_b32_e64 v40, v146, v40, s[44:45]
	v_cndmask_b32_e64 v43, v43, v156, s[44:45]
	v_cndmask_b32_e64 v41, v156, v41, s[44:45]
	v_cndmask_b32_e64 v145, v44, v45, s[42:43]
	v_cndmask_b32_e64 v147, v46, v47, s[42:43]
	s_nop 1
	v_mov_b32_dpp v146, v145 quad_perm:[1,0,3,2] row_mask:0xf bank_mask:0xf
	v_mov_b32_dpp v156, v147 quad_perm:[1,0,3,2] row_mask:0xf bank_mask:0xf
	v_cndmask_b32_e64 v45, v45, v146, s[42:43]
	v_cndmask_b32_e64 v44, v146, v44, s[42:43]
	v_cndmask_b32_e64 v47, v47, v156, s[42:43]
	v_cndmask_b32_e64 v46, v156, v46, s[42:43]
	v_cndmask_b32_e64 v145, v44, v46, s[44:45]
	v_cndmask_b32_e64 v147, v45, v47, s[44:45]
	s_nop 1
	v_mov_b32_dpp v146, v145 quad_perm:[2,3,0,1] row_mask:0xf bank_mask:0xf
	v_mov_b32_dpp v156, v147 quad_perm:[2,3,0,1] row_mask:0xf bank_mask:0xf
	v_cndmask_b32_e64 v46, v46, v146, s[44:45]
	v_cndmask_b32_e64 v44, v146, v44, s[44:45]
	v_cndmask_b32_e64 v47, v47, v156, s[44:45]
	v_cndmask_b32_e64 v45, v156, v45, s[44:45]
	v_cndmask_b32_e64 v145, v48, v49, s[42:43]
	v_cndmask_b32_e64 v147, v50, v51, s[42:43]
	s_nop 1
	v_mov_b32_dpp v146, v145 quad_perm:[1,0,3,2] row_mask:0xf bank_mask:0xf
	v_mov_b32_dpp v156, v147 quad_perm:[1,0,3,2] row_mask:0xf bank_mask:0xf
	v_cndmask_b32_e64 v49, v49, v146, s[42:43]
	v_cndmask_b32_e64 v48, v146, v48, s[42:43]
	v_cndmask_b32_e64 v51, v51, v156, s[42:43]
	v_cndmask_b32_e64 v50, v156, v50, s[42:43]
	v_cndmask_b32_e64 v145, v48, v50, s[44:45]
	v_cndmask_b32_e64 v147, v49, v51, s[44:45]
	s_nop 1
	v_mov_b32_dpp v146, v145 quad_perm:[2,3,0,1] row_mask:0xf bank_mask:0xf
	v_mov_b32_dpp v156, v147 quad_perm:[2,3,0,1] row_mask:0xf bank_mask:0xf
	v_cndmask_b32_e64 v50, v50, v146, s[44:45]
	v_cndmask_b32_e64 v48, v146, v48, s[44:45]
	v_cndmask_b32_e64 v51, v51, v156, s[44:45]
	v_cndmask_b32_e64 v49, v156, v49, s[44:45]
	v_cndmask_b32_e64 v145, v52, v53, s[42:43]
	v_cndmask_b32_e64 v147, v54, v55, s[42:43]
	s_nop 1
	v_mov_b32_dpp v146, v145 quad_perm:[1,0,3,2] row_mask:0xf bank_mask:0xf
	v_mov_b32_dpp v156, v147 quad_perm:[1,0,3,2] row_mask:0xf bank_mask:0xf
	v_cndmask_b32_e64 v53, v53, v146, s[42:43]
	v_cndmask_b32_e64 v52, v146, v52, s[42:43]
	v_cndmask_b32_e64 v55, v55, v156, s[42:43]
	v_cndmask_b32_e64 v54, v156, v54, s[42:43]
	v_cndmask_b32_e64 v145, v52, v54, s[44:45]
	v_cndmask_b32_e64 v147, v53, v55, s[44:45]
	s_nop 1
	v_mov_b32_dpp v146, v145 quad_perm:[2,3,0,1] row_mask:0xf bank_mask:0xf
	v_mov_b32_dpp v156, v147 quad_perm:[2,3,0,1] row_mask:0xf bank_mask:0xf
	v_cndmask_b32_e64 v54, v54, v146, s[44:45]
	v_cndmask_b32_e64 v52, v146, v52, s[44:45]
	v_cndmask_b32_e64 v55, v55, v156, s[44:45]
	v_cndmask_b32_e64 v53, v156, v53, s[44:45]
; __device__ __forceinline__ void hg_seq(const Frame& F, unsigned char* ws, const float* s0, float* sout, float* Og, int seq, bool sample, int vs_base, int nvs) {
;     ...
;     if (sample && active) {
; #pragma unroll
;         for (int kb = 0; kb < 8; ++kb)
; #pragma unroll
;             for (int i = 0; i < 4; ++i) S[kb][i] = s0[((size_t)seq * 128 + 16 * kb + 4 * q + i) * 128 + 16 * vs + r];
;     } else {
;     ...
;     if (active) {
; #pragma unroll
;     for (int kb = 0; kb < 8; ++kb)
; #pragma unroll
;         for (int i = 0; i < 4; ++i) sout[((size_t)seq * 128 + 16 * kb + 4 * q + i) * 128 + 16 * vs + r] = S[kb][i];
;     }
	v_cndmask_b32_e64 v145, v56, v57, s[42:43]
	v_cndmask_b32_e64 v147, v58, v59, s[42:43]
	s_nop 1
	v_mov_b32_dpp v146, v145 quad_perm:[1,0,3,2] row_mask:0xf bank_mask:0xf
	v_mov_b32_dpp v156, v147 quad_perm:[1,0,3,2] row_mask:0xf bank_mask:0xf
	v_cndmask_b32_e64 v57, v57, v146, s[42:43]
	v_cndmask_b32_e64 v56, v146, v56, s[42:43]
	v_cndmask_b32_e64 v59, v59, v156, s[42:43]
	v_cndmask_b32_e64 v58, v156, v58, s[42:43]
	v_cndmask_b32_e64 v145, v56, v58, s[44:45]
	v_cndmask_b32_e64 v147, v57, v59, s[44:45]
	s_nop 1
	v_mov_b32_dpp v146, v145 quad_perm:[2,3,0,1] row_mask:0xf bank_mask:0xf
	v_mov_b32_dpp v156, v147 quad_perm:[2,3,0,1] row_mask:0xf bank_mask:0xf
	v_cndmask_b32_e64 v58, v58, v146, s[44:45]
	v_cndmask_b32_e64 v56, v146, v56, s[44:45]
	v_cndmask_b32_e64 v59, v59, v156, s[44:45]
	v_cndmask_b32_e64 v57, v156, v57, s[44:45]
	v_cndmask_b32_e64 v145, v60, v61, s[42:43]
	v_cndmask_b32_e64 v147, v62, v63, s[42:43]
	s_nop 1
	v_mov_b32_dpp v146, v145 quad_perm:[1,0,3,2] row_mask:0xf bank_mask:0xf
	v_mov_b32_dpp v156, v147 quad_perm:[1,0,3,2] row_mask:0xf bank_mask:0xf
	v_cndmask_b32_e64 v61, v61, v146, s[42:43]
	v_cndmask_b32_e64 v60, v146, v60, s[42:43]
	v_cndmask_b32_e64 v63, v63, v156, s[42:43]
	v_cndmask_b32_e64 v62, v156, v62, s[42:43]
	v_cndmask_b32_e64 v145, v60, v62, s[44:45]
	v_cndmask_b32_e64 v147, v61, v63, s[44:45]
	s_nop 1
	v_mov_b32_dpp v146, v145 quad_perm:[2,3,0,1] row_mask:0xf bank_mask:0xf
	v_mov_b32_dpp v156, v147 quad_perm:[2,3,0,1] row_mask:0xf bank_mask:0xf
	v_cndmask_b32_e64 v62, v62, v146, s[44:45]
	v_cndmask_b32_e64 v60, v146, v60, s[44:45]
	v_cndmask_b32_e64 v63, v63, v156, s[44:45]
	v_cndmask_b32_e64 v61, v156, v61, s[44:45]
	v_cndmask_b32_e64 v145, v64, v65, s[42:43]
	v_cndmask_b32_e64 v147, v66, v67, s[42:43]
	s_nop 1
	v_mov_b32_dpp v146, v145 quad_perm:[1,0,3,2] row_mask:0xf bank_mask:0xf
	v_mov_b32_dpp v156, v147 quad_perm:[1,0,3,2] row_mask:0xf bank_mask:0xf
	v_cndmask_b32_e64 v65, v65, v146, s[42:43]
	v_cndmask_b32_e64 v64, v146, v64, s[42:43]
	v_cndmask_b32_e64 v67, v67, v156, s[42:43]
	v_cndmask_b32_e64 v66, v156, v66, s[42:43]
	v_cndmask_b32_e64 v145, v64, v66, s[44:45]
	v_cndmask_b32_e64 v147, v65, v67, s[44:45]
	s_nop 1
	v_mov_b32_dpp v146, v145 quad_perm:[2,3,0,1] row_mask:0xf bank_mask:0xf
	v_mov_b32_dpp v156, v147 quad_perm:[2,3,0,1] row_mask:0xf bank_mask:0xf
	v_cndmask_b32_e64 v66, v66, v146, s[44:45]
	v_cndmask_b32_e64 v64, v146, v64, s[44:45]
	v_cndmask_b32_e64 v67, v67, v156, s[44:45]
	v_cndmask_b32_e64 v65, v156, v65, s[44:45]
	global_store_dwordx4 v200, v[36:39], s[10:11]
	global_store_dwordx4 v201, v[40:43], s[10:11]
	global_store_dwordx4 v202, v[44:47], s[10:11]
	global_store_dwordx4 v203, v[48:51], s[10:11]
	global_store_dwordx4 v204, v[52:55], s[10:11]
	global_store_dwordx4 v205, v[56:59], s[10:11]
	global_store_dwordx4 v206, v[60:63], s[10:11]
	global_store_dwordx4 v207, v[64:67], s[10:11]
	s_add_u32 s10, s10, s34
	s_addc_u32 s11, s11, 0
	s_waitcnt vmcnt(12)
	global_load_dwordx4 v[36:39], v200, s[8:9]
	global_load_dwordx4 v[40:43], v201, s[8:9]
	global_load_dwordx4 v[44:47], v202, s[8:9]
	global_load_dwordx4 v[48:51], v203, s[8:9]
	global_load_dwordx4 v[52:55], v204, s[8:9]
	global_load_dwordx4 v[56:59], v205, s[8:9]
	global_load_dwordx4 v[60:63], v206, s[8:9]
	global_load_dwordx4 v[64:67], v207, s[8:9]
	s_add_u32 s8, s8, s34
	s_addc_u32 s9, s9, 0
	v_cndmask_b32_e64 v145, v4, v5, s[42:43]
	v_cndmask_b32_e64 v147, v6, v7, s[42:43]
	s_nop 1
	v_mov_b32_dpp v146, v145 quad_perm:[1,0,3,2] row_mask:0xf bank_mask:0xf
	v_mov_b32_dpp v156, v147 quad_perm:[1,0,3,2] row_mask:0xf bank_mask:0xf
	v_cndmask_b32_e64 v5, v5, v146, s[42:43]
	v_cndmask_b32_e64 v4, v146, v4, s[42:43]
	v_cndmask_b32_e64 v7, v7, v156, s[42:43]
	v_cndmask_b32_e64 v6, v156, v6, s[42:43]
	v_cndmask_b32_e64 v145, v4, v6, s[44:45]
	v_cndmask_b32_e64 v147, v5, v7, s[44:45]
	s_nop 1
	v_mov_b32_dpp v146, v145 quad_perm:[2,3,0,1] row_mask:0xf bank_mask:0xf
	v_mov_b32_dpp v156, v147 quad_perm:[2,3,0,1] row_mask:0xf bank_mask:0xf
	v_cndmask_b32_e64 v6, v6, v146, s[44:45]
	v_cndmask_b32_e64 v4, v146, v4, s[44:45]
	v_cndmask_b32_e64 v7, v7, v156, s[44:45]
	v_cndmask_b32_e64 v5, v156, v5, s[44:45]
	v_cndmask_b32_e64 v145, v8, v9, s[42:43]
	v_cndmask_b32_e64 v147, v10, v11, s[42:43]
	s_nop 1
	v_mov_b32_dpp v146, v145 quad_perm:[1,0,3,2] row_mask:0xf bank_mask:0xf
	v_mov_b32_dpp v156, v147 quad_perm:[1,0,3,2] row_mask:0xf bank_mask:0xf
	v_cndmask_b32_e64 v9, v9, v146, s[42:43]
	v_cndmask_b32_e64 v8, v146, v8, s[42:43]
	v_cndmask_b32_e64 v11, v11, v156, s[42:43]
	v_cndmask_b32_e64 v10, v156, v10, s[42:43]
	v_cndmask_b32_e64 v145, v8, v10, s[44:45]
	v_cndmask_b32_e64 v147, v9, v11, s[44:45]
	s_nop 1
	v_mov_b32_dpp v146, v145 quad_perm:[2,3,0,1] row_mask:0xf bank_mask:0xf
	v_mov_b32_dpp v156, v147 quad_perm:[2,3,0,1] row_mask:0xf bank_mask:0xf
	v_cndmask_b32_e64 v10, v10, v146, s[44:45]
	v_cndmask_b32_e64 v8, v146, v8, s[44:45]
	v_cndmask_b32_e64 v11, v11, v156, s[44:45]
	v_cndmask_b32_e64 v9, v156, v9, s[44:45]
	v_cndmask_b32_e64 v145, v12, v13, s[42:43]
	v_cndmask_b32_e64 v147, v14, v15, s[42:43]
	s_nop 1
	v_mov_b32_dpp v146, v145 quad_perm:[1,0,3,2] row_mask:0xf bank_mask:0xf
	v_mov_b32_dpp v156, v147 quad_perm:[1,0,3,2] row_mask:0xf bank_mask:0xf
	v_cndmask_b32_e64 v13, v13, v146, s[42:43]
	v_cndmask_b32_e64 v12, v146, v12, s[42:43]
	v_cndmask_b32_e64 v15, v15, v156, s[42:43]
	v_cndmask_b32_e64 v14, v156, v14, s[42:43]
	v_cndmask_b32_e64 v145, v12, v14, s[44:45]
	v_cndmask_b32_e64 v147, v13, v15, s[44:45]
	s_nop 1
	v_mov_b32_dpp v146, v145 quad_perm:[2,3,0,1] row_mask:0xf bank_mask:0xf
	v_mov_b32_dpp v156, v147 quad_perm:[2,3,0,1] row_mask:0xf bank_mask:0xf
; #define LAS __attribute__((address_space(3)))
; __device__ __forceinline__ unsigned pk2(float lo, float hi) { const f32x2_t_ v = {lo, hi}; return __builtin_bit_cast(unsigned, __builtin_convertvector(v, bf16x2_t_)); }
; __device__ __forceinline__ void hg_chunk(const LAS unsigned char* sl, f32x4 (&S)[8], float* Orow, int nvalid, int vs, int lane) {
;     const int r = lane & 15, q = lane >> 4;
;     const bf16x8 vfr = *(const LAS bf16x8*)(sl + 16384 + ((vs * 64 + lane) << 4));
;     f32x4 o0 = {0.f, 0.f, 0.f, 0.f}, o1 = {0.f, 0.f, 0.f, 0.f};
;     { const bf16x8 s0 = *(const LAS bf16x8*)(sl + 24576 + (lane << 4)), s1 = *(const LAS bf16x8*)(sl + 24576 + ((64 + lane) << 4));
;       o0 = __builtin_amdgcn_mfma_f32_16x16x32_bf16(s0, vfr, o0, 0, 0, 0); o1 = __builtin_amdgcn_mfma_f32_16x16x32_bf16(s1, vfr, o1, 0, 0, 0); }
; #pragma unroll
;     for (int m = 0; m < 4; ++m) {
;         v4u sw; sw.x = pk2(S[2 * m][0], S[2 * m][1]); sw.y = pk2(S[2 * m][2], S[2 * m][3]); sw.z = pk2(S[2 * m + 1][0], S[2 * m + 1][1]); sw.w = pk2(S[2 * m + 1][2], S[2 * m + 1][3]);
;         const bf16x8 sb = __builtin_bit_cast(bf16x8, sw);
;         const bf16x8 a0 = *(const LAS bf16x8*)(sl + ((m * 64 + lane) << 4)), a1 = *(const LAS bf16x8*)(sl + (((4 + m) * 64 + lane) << 4));
;         o0 = __builtin_amdgcn_mfma_f32_16x16x32_bf16(a0, sb, o0, 0, 0, 0); o1 = __builtin_amdgcn_mfma_f32_16x16x32_bf16(a1, sb, o1, 0, 0, 0);
;     }
; #pragma unroll
;     for (int i = 0; i < 4; ++i) { const int c0 = 4 * q + i;
;         if (c0 < nvalid) Orow[(size_t)c0 * DA + 16 * vs + r] = o0[i];
;         if (c0 + 16 < nvalid) Orow[(size_t)(c0 + 16) * DA + 16 * vs + r] = o1[i]; }
; #pragma unroll
;     for (int kb = 0; kb < 8; ++kb) { const f32x4 d = *(const LAS f32x4*)(sl + 26624 + ((16 * kb + 4 * q) << 2));
;         const bf16x8 ke = *(const LAS bf16x8*)(sl + 8192 + ((kb * 64 + lane) << 4));
;         S[kb] = __builtin_amdgcn_mfma_f32_16x16x32_bf16(ke, vfr, S[kb] * d, 0, 0, 0); }
; __device__ __forceinline__ void hg_seq(const Frame& F, unsigned char* ws, const float* s0, float* sout, float* Og, int seq, bool sample, int vs_base, int nvs) {
;     ...
;     if (sample && active) {
; #pragma unroll
;         for (int kb = 0; kb < 8; ++kb)
; #pragma unroll
;             for (int i = 0; i < 4; ++i) S[kb][i] = s0[((size_t)seq * 128 + 16 * kb + 4 * q + i) * 128 + 16 * vs + r];
;     } else {
	v_cndmask_b32_e64 v14, v14, v146, s[44:45]
	v_cndmask_b32_e64 v12, v146, v12, s[44:45]
	v_cndmask_b32_e64 v15, v15, v156, s[44:45]
	v_cndmask_b32_e64 v13, v156, v13, s[44:45]
	v_cndmask_b32_e64 v145, v16, v17, s[42:43]
	v_cndmask_b32_e64 v147, v18, v19, s[42:43]
	s_nop 1
	v_mov_b32_dpp v146, v145 quad_perm:[1,0,3,2] row_mask:0xf bank_mask:0xf
	v_mov_b32_dpp v156, v147 quad_perm:[1,0,3,2] row_mask:0xf bank_mask:0xf
	v_cndmask_b32_e64 v17, v17, v146, s[42:43]
	v_cndmask_b32_e64 v16, v146, v16, s[42:43]
	v_cndmask_b32_e64 v19, v19, v156, s[42:43]
	v_cndmask_b32_e64 v18, v156, v18, s[42:43]
	v_cndmask_b32_e64 v145, v16, v18, s[44:45]
	v_cndmask_b32_e64 v147, v17, v19, s[44:45]
	s_nop 1
	v_mov_b32_dpp v146, v145 quad_perm:[2,3,0,1] row_mask:0xf bank_mask:0xf
	v_mov_b32_dpp v156, v147 quad_perm:[2,3,0,1] row_mask:0xf bank_mask:0xf
	v_cndmask_b32_e64 v18, v18, v146, s[44:45]
	v_cndmask_b32_e64 v16, v146, v16, s[44:45]
	v_cndmask_b32_e64 v19, v19, v156, s[44:45]
	v_cndmask_b32_e64 v17, v156, v17, s[44:45]
	v_cndmask_b32_e64 v145, v20, v21, s[42:43]
	v_cndmask_b32_e64 v147, v22, v23, s[42:43]
	s_nop 1
	v_mov_b32_dpp v146, v145 quad_perm:[1,0,3,2] row_mask:0xf bank_mask:0xf
	v_mov_b32_dpp v156, v147 quad_perm:[1,0,3,2] row_mask:0xf bank_mask:0xf
	v_cndmask_b32_e64 v21, v21, v146, s[42:43]
	v_cndmask_b32_e64 v20, v146, v20, s[42:43]
	v_cndmask_b32_e64 v23, v23, v156, s[42:43]
	v_cndmask_b32_e64 v22, v156, v22, s[42:43]
	v_cndmask_b32_e64 v145, v20, v22, s[44:45]
	v_cndmask_b32_e64 v147, v21, v23, s[44:45]
	s_nop 1
	v_mov_b32_dpp v146, v145 quad_perm:[2,3,0,1] row_mask:0xf bank_mask:0xf
	v_mov_b32_dpp v156, v147 quad_perm:[2,3,0,1] row_mask:0xf bank_mask:0xf
	v_cndmask_b32_e64 v22, v22, v146, s[44:45]
	v_cndmask_b32_e64 v20, v146, v20, s[44:45]
	v_cndmask_b32_e64 v23, v23, v156, s[44:45]
	v_cndmask_b32_e64 v21, v156, v21, s[44:45]
	v_cndmask_b32_e64 v145, v24, v25, s[42:43]
	v_cndmask_b32_e64 v147, v26, v27, s[42:43]
	s_nop 1
	v_mov_b32_dpp v146, v145 quad_perm:[1,0,3,2] row_mask:0xf bank_mask:0xf
	v_mov_b32_dpp v156, v147 quad_perm:[1,0,3,2] row_mask:0xf bank_mask:0xf
	v_cndmask_b32_e64 v25, v25, v146, s[42:43]
	v_cndmask_b32_e64 v24, v146, v24, s[42:43]
	v_cndmask_b32_e64 v27, v27, v156, s[42:43]
	v_cndmask_b32_e64 v26, v156, v26, s[42:43]
	v_cndmask_b32_e64 v145, v24, v26, s[44:45]
	v_cndmask_b32_e64 v147, v25, v27, s[44:45]
	s_nop 1
	v_mov_b32_dpp v146, v145 quad_perm:[2,3,0,1] row_mask:0xf bank_mask:0xf
	v_mov_b32_dpp v156, v147 quad_perm:[2,3,0,1] row_mask:0xf bank_mask:0xf
	v_cndmask_b32_e64 v26, v26, v146, s[44:45]
	v_cndmask_b32_e64 v24, v146, v24, s[44:45]
	v_cndmask_b32_e64 v27, v27, v156, s[44:45]
	v_cndmask_b32_e64 v25, v156, v25, s[44:45]
	v_cndmask_b32_e64 v145, v28, v29, s[42:43]
	v_cndmask_b32_e64 v147, v30, v31, s[42:43]
	s_nop 1
	v_mov_b32_dpp v146, v145 quad_perm:[1,0,3,2] row_mask:0xf bank_mask:0xf
	v_mov_b32_dpp v156, v147 quad_perm:[1,0,3,2] row_mask:0xf bank_mask:0xf
	v_cndmask_b32_e64 v29, v29, v146, s[42:43]
	v_cndmask_b32_e64 v28, v146, v28, s[42:43]
	v_cndmask_b32_e64 v31, v31, v156, s[42:43]
	v_cndmask_b32_e64 v30, v156, v30, s[42:43]
	v_cndmask_b32_e64 v145, v28, v30, s[44:45]
	v_cndmask_b32_e64 v147, v29, v31, s[44:45]
	s_nop 1
	v_mov_b32_dpp v146, v145 quad_perm:[2,3,0,1] row_mask:0xf bank_mask:0xf
	v_mov_b32_dpp v156, v147 quad_perm:[2,3,0,1] row_mask:0xf bank_mask:0xf
	v_cndmask_b32_e64 v30, v30, v146, s[44:45]
	v_cndmask_b32_e64 v28, v146, v28, s[44:45]
	v_cndmask_b32_e64 v31, v31, v156, s[44:45]
	v_cndmask_b32_e64 v29, v156, v29, s[44:45]
	v_cndmask_b32_e64 v145, v32, v33, s[42:43]
	v_cndmask_b32_e64 v147, v34, v35, s[42:43]
	s_nop 1
	v_mov_b32_dpp v146, v145 quad_perm:[1,0,3,2] row_mask:0xf bank_mask:0xf
	v_mov_b32_dpp v156, v147 quad_perm:[1,0,3,2] row_mask:0xf bank_mask:0xf
	v_cndmask_b32_e64 v33, v33, v146, s[42:43]
	v_cndmask_b32_e64 v32, v146, v32, s[42:43]
	v_cndmask_b32_e64 v35, v35, v156, s[42:43]
	v_cndmask_b32_e64 v34, v156, v34, s[42:43]
	v_cndmask_b32_e64 v145, v32, v34, s[44:45]
	v_cndmask_b32_e64 v147, v33, v35, s[44:45]
	s_nop 1
	v_mov_b32_dpp v146, v145 quad_perm:[2,3,0,1] row_mask:0xf bank_mask:0xf
	v_mov_b32_dpp v156, v147 quad_perm:[2,3,0,1] row_mask:0xf bank_mask:0xf
	v_cndmask_b32_e64 v34, v34, v146, s[44:45]
	v_cndmask_b32_e64 v32, v146, v32, s[44:45]
	v_cndmask_b32_e64 v35, v35, v156, s[44:45]
	v_cndmask_b32_e64 v33, v156, v33, s[44:45]
	v_add_u32_e32 v1, 0xd800, v142
	v_add_u32_e32 v2, 0xd800, v143
	v_add_u32_e32 v3, 0xd800, v144
	ds_read_b128 v[164:167], v3 offset:26624
	ds_read_b128 v[168:171], v3 offset:26688
	ds_read_b128 v[172:175], v3 offset:26752
	ds_read_b128 v[176:179], v3 offset:26816
	ds_read_b128 v[180:183], v3 offset:26880
	ds_read_b128 v[184:187], v3 offset:26944
	ds_read_b128 v[148:151], v3 offset:27008
	ds_read_b128 v[152:155], v3 offset:27072
	ds_read_b128 v[84:87], v2 offset:16384
	ds_read_b128 v[88:91], v1 offset:24576
	ds_read_b128 v[92:95], v1 offset:0
	ds_read_b128 v[96:99], v1 offset:1024
	ds_read_b128 v[100:103], v1 offset:2048
	ds_read_b128 v[104:107], v1 offset:3072
	v_cvt_pk_bf16_f32 v68, v4, v5
	v_cvt_pk_bf16_f32 v69, v6, v7
	v_cvt_pk_bf16_f32 v70, v8, v9
	v_cvt_pk_bf16_f32 v71, v10, v11
	v_cvt_pk_bf16_f32 v72, v12, v13
	v_cvt_pk_bf16_f32 v73, v14, v15
	v_cvt_pk_bf16_f32 v74, v16, v17
	v_cvt_pk_bf16_f32 v75, v18, v19
	v_cvt_pk_bf16_f32 v76, v20, v21
	v_cvt_pk_bf16_f32 v77, v22, v23
	v_cvt_pk_bf16_f32 v78, v24, v25
	v_cvt_pk_bf16_f32 v79, v26, v27
	v_cvt_pk_bf16_f32 v80, v28, v29
	v_cvt_pk_bf16_f32 v81, v30, v31
	v_cvt_pk_bf16_f32 v82, v32, v33
	v_cvt_pk_bf16_f32 v83, v34, v35
	s_waitcnt lgkmcnt(6)
; #define LAS __attribute__((address_space(3)))
; __device__ __forceinline__ unsigned pk2(float lo, float hi) { const f32x2_t_ v = {lo, hi}; return __builtin_bit_cast(unsigned, __builtin_convertvector(v, bf16x2_t_)); }
; __device__ __forceinline__ void hg_chunk(const LAS unsigned char* sl, f32x4 (&S)[8], float* Orow, int nvalid, int vs, int lane) {
;     ...
;     { const bf16x8 s0 = *(const LAS bf16x8*)(sl + 24576 + (lane << 4)), s1 = *(const LAS bf16x8*)(sl + 24576 + ((64 + lane) << 4));
;       o0 = __builtin_amdgcn_mfma_f32_16x16x32_bf16(s0, vfr, o0, 0, 0, 0); o1 = __builtin_amdgcn_mfma_f32_16x16x32_bf16(s1, vfr, o1, 0, 0, 0); }
; #pragma unroll
;     for (int m = 0; m < 4; ++m) {
;         v4u sw; sw.x = pk2(S[2 * m][0], S[2 * m][1]); sw.y = pk2(S[2 * m][2], S[2 * m][3]); sw.z = pk2(S[2 * m + 1][0], S[2 * m + 1][1]); sw.w = pk2(S[2 * m + 1][2], S[2 * m + 1][3]);
;         const bf16x8 sb = __builtin_bit_cast(bf16x8, sw);
;         const bf16x8 a0 = *(const LAS bf16x8*)(sl + ((m * 64 + lane) << 4)), a1 = *(const LAS bf16x8*)(sl + (((4 + m) * 64 + lane) << 4));
;         o0 = __builtin_amdgcn_mfma_f32_16x16x32_bf16(a0, sb, o0, 0, 0, 0); o1 = __builtin_amdgcn_mfma_f32_16x16x32_bf16(a1, sb, o1, 0, 0, 0);
;     }
; #pragma unroll
;     for (int i = 0; i < 4; ++i) { const int c0 = 4 * q + i;
;         if (c0 < nvalid) Orow[(size_t)c0 * DA + 16 * vs + r] = o0[i];
;         if (c0 + 16 < nvalid) Orow[(size_t)(c0 + 16) * DA + 16 * vs + r] = o1[i]; }
; #pragma unroll
;     for (int kb = 0; kb < 8; ++kb) { const f32x4 d = *(const LAS f32x4*)(sl + 26624 + ((16 * kb + 4 * q) << 2));
;         const bf16x8 ke = *(const LAS bf16x8*)(sl + 8192 + ((kb * 64 + lane) << 4));
;         S[kb] = __builtin_amdgcn_mfma_f32_16x16x32_bf16(ke, vfr, S[kb] * d, 0, 0, 0); }
; __device__ __forceinline__ void hg_seq(const Frame& F, unsigned char* ws, const float* s0, float* sout, float* Og, int seq, bool sample, int vs_base, int nvs) {
;     ...
;     if (active) {
; #pragma unroll
;     for (int kb = 0; kb < 8; ++kb)
; #pragma unroll
;         for (int i = 0; i < 4; ++i) sout[((size_t)seq * 128 + 16 * kb + 4 * q + i) * 128 + 16 * vs + r] = S[kb][i];
;     }
	v_pk_mul_f32 v[4:5], v[4:5], v[164:165]
	v_pk_mul_f32 v[6:7], v[6:7], v[166:167]
	v_pk_mul_f32 v[8:9], v[8:9], v[168:169]
	v_pk_mul_f32 v[10:11], v[10:11], v[170:171]
	v_pk_mul_f32 v[12:13], v[12:13], v[172:173]
	v_pk_mul_f32 v[14:15], v[14:15], v[174:175]
	v_pk_mul_f32 v[16:17], v[16:17], v[176:177]
	v_pk_mul_f32 v[18:19], v[18:19], v[178:179]
	v_pk_mul_f32 v[20:21], v[20:21], v[180:181]
	v_pk_mul_f32 v[22:23], v[22:23], v[182:183]
	v_pk_mul_f32 v[24:25], v[24:25], v[184:185]
	v_pk_mul_f32 v[26:27], v[26:27], v[186:187]
	v_pk_mul_f32 v[28:29], v[28:29], v[148:149]
	v_pk_mul_f32 v[30:31], v[30:31], v[150:151]
	v_pk_mul_f32 v[32:33], v[32:33], v[152:153]
	v_pk_mul_f32 v[34:35], v[34:35], v[154:155]
	ds_read_b128 v[108:111], v1 offset:8192
	ds_read_b128 v[112:115], v1 offset:9216
	ds_read_b128 v[116:119], v1 offset:10240
	ds_read_b128 v[120:123], v1 offset:11264
	ds_read_b128 v[124:127], v1 offset:12288
	ds_read_b128 v[128:131], v1 offset:13312
	ds_read_b128 v[132:135], v1 offset:14336
	ds_read_b128 v[136:139], v1 offset:15360
	s_waitcnt lgkmcnt(12)
	v_mfma_f32_16x16x32_bf16 v[196:199], v[88:91], v[84:87], 0
	s_waitcnt lgkmcnt(11)
	v_mfma_f32_16x16x32_bf16 v[196:199], v[92:95], v[68:71], v[196:199]
	s_waitcnt lgkmcnt(10)
	v_mfma_f32_16x16x32_bf16 v[196:199], v[96:99], v[72:75], v[196:199]
	s_waitcnt lgkmcnt(9)
	v_mfma_f32_16x16x32_bf16 v[196:199], v[100:103], v[76:79], v[196:199]
	s_waitcnt lgkmcnt(8)
	v_mfma_f32_16x16x32_bf16 v[196:199], v[104:107], v[80:83], v[196:199]
	s_waitcnt lgkmcnt(7)
	v_mfma_f32_16x16x32_bf16 v[4:7], v[108:111], v[84:87], v[4:7]
	s_waitcnt lgkmcnt(6)
	v_mfma_f32_16x16x32_bf16 v[8:11], v[112:115], v[84:87], v[8:11]
	s_waitcnt lgkmcnt(5)
	v_mfma_f32_16x16x32_bf16 v[12:15], v[116:119], v[84:87], v[12:15]
	s_waitcnt lgkmcnt(4)
	v_mfma_f32_16x16x32_bf16 v[16:19], v[120:123], v[84:87], v[16:19]
	s_waitcnt lgkmcnt(3)
	v_mfma_f32_16x16x32_bf16 v[20:23], v[124:127], v[84:87], v[20:23]
	s_waitcnt lgkmcnt(2)
	v_mfma_f32_16x16x32_bf16 v[24:27], v[128:131], v[84:87], v[24:27]
	s_waitcnt lgkmcnt(1)
	v_mfma_f32_16x16x32_bf16 v[28:31], v[132:135], v[84:87], v[28:31]
	s_waitcnt lgkmcnt(0)
	v_mfma_f32_16x16x32_bf16 v[32:35], v[136:139], v[84:87], v[32:35]
	s_mov_b32 exec_hi, 0
	global_store_dword v208, v196, s[12:13]
	global_store_dword v208, v197, s[12:13] offset:2048
	global_store_dword v209, v198, s[12:13]
	global_store_dword v209, v199, s[12:13] offset:2048
	s_mov_b64 exec, -1
	s_add_u32 s12, s12, 0x80000
	s_addc_u32 s13, s13, 0
	s_nop 7
	v_cndmask_b32_e64 v145, v4, v5, s[42:43]
	v_cndmask_b32_e64 v147, v6, v7, s[42:43]
	s_nop 1
	v_mov_b32_dpp v146, v145 quad_perm:[1,0,3,2] row_mask:0xf bank_mask:0xf
	v_mov_b32_dpp v156, v147 quad_perm:[1,0,3,2] row_mask:0xf bank_mask:0xf
	v_cndmask_b32_e64 v5, v5, v146, s[42:43]
	v_cndmask_b32_e64 v4, v146, v4, s[42:43]
	v_cndmask_b32_e64 v7, v7, v156, s[42:43]
	v_cndmask_b32_e64 v6, v156, v6, s[42:43]
	v_cndmask_b32_e64 v145, v4, v6, s[44:45]
	v_cndmask_b32_e64 v147, v5, v7, s[44:45]
	s_nop 1
	v_mov_b32_dpp v146, v145 quad_perm:[2,3,0,1] row_mask:0xf bank_mask:0xf
	v_mov_b32_dpp v156, v147 quad_perm:[2,3,0,1] row_mask:0xf bank_mask:0xf
	v_cndmask_b32_e64 v6, v6, v146, s[44:45]
	v_cndmask_b32_e64 v4, v146, v4, s[44:45]
	v_cndmask_b32_e64 v7, v7, v156, s[44:45]
	v_cndmask_b32_e64 v5, v156, v5, s[44:45]
	v_cndmask_b32_e64 v145, v8, v9, s[42:43]
	v_cndmask_b32_e64 v147, v10, v11, s[42:43]
	s_nop 1
	v_mov_b32_dpp v146, v145 quad_perm:[1,0,3,2] row_mask:0xf bank_mask:0xf
	v_mov_b32_dpp v156, v147 quad_perm:[1,0,3,2] row_mask:0xf bank_mask:0xf
	v_cndmask_b32_e64 v9, v9, v146, s[42:43]
	v_cndmask_b32_e64 v8, v146, v8, s[42:43]
	v_cndmask_b32_e64 v11, v11, v156, s[42:43]
	v_cndmask_b32_e64 v10, v156, v10, s[42:43]
	v_cndmask_b32_e64 v145, v8, v10, s[44:45]
	v_cndmask_b32_e64 v147, v9, v11, s[44:45]
	s_nop 1
	v_mov_b32_dpp v146, v145 quad_perm:[2,3,0,1] row_mask:0xf bank_mask:0xf
	v_mov_b32_dpp v156, v147 quad_perm:[2,3,0,1] row_mask:0xf bank_mask:0xf
	v_cndmask_b32_e64 v10, v10, v146, s[44:45]
	v_cndmask_b32_e64 v8, v146, v8, s[44:45]
	v_cndmask_b32_e64 v11, v11, v156, s[44:45]
	v_cndmask_b32_e64 v9, v156, v9, s[44:45]
	v_cndmask_b32_e64 v145, v12, v13, s[42:43]
	v_cndmask_b32_e64 v147, v14, v15, s[42:43]
	s_nop 1
	v_mov_b32_dpp v146, v145 quad_perm:[1,0,3,2] row_mask:0xf bank_mask:0xf
	v_mov_b32_dpp v156, v147 quad_perm:[1,0,3,2] row_mask:0xf bank_mask:0xf
	v_cndmask_b32_e64 v13, v13, v146, s[42:43]
	v_cndmask_b32_e64 v12, v146, v12, s[42:43]
	v_cndmask_b32_e64 v15, v15, v156, s[42:43]
	v_cndmask_b32_e64 v14, v156, v14, s[42:43]
	v_cndmask_b32_e64 v145, v12, v14, s[44:45]
	v_cndmask_b32_e64 v147, v13, v15, s[44:45]
	s_nop 1
	v_mov_b32_dpp v146, v145 quad_perm:[2,3,0,1] row_mask:0xf bank_mask:0xf
	v_mov_b32_dpp v156, v147 quad_perm:[2,3,0,1] row_mask:0xf bank_mask:0xf
	v_cndmask_b32_e64 v14, v14, v146, s[44:45]
	v_cndmask_b32_e64 v12, v146, v12, s[44:45]
	v_cndmask_b32_e64 v15, v15, v156, s[44:45]
	v_cndmask_b32_e64 v13, v156, v13, s[44:45]
	v_cndmask_b32_e64 v145, v16, v17, s[42:43]
	v_cndmask_b32_e64 v147, v18, v19, s[42:43]
	s_nop 1
	v_mov_b32_dpp v146, v145 quad_perm:[1,0,3,2] row_mask:0xf bank_mask:0xf
	v_mov_b32_dpp v156, v147 quad_perm:[1,0,3,2] row_mask:0xf bank_mask:0xf
	v_cndmask_b32_e64 v17, v17, v146, s[42:43]
	v_cndmask_b32_e64 v16, v146, v16, s[42:43]
	v_cndmask_b32_e64 v19, v19, v156, s[42:43]
	v_cndmask_b32_e64 v18, v156, v18, s[42:43]
	v_cndmask_b32_e64 v145, v16, v18, s[44:45]
	v_cndmask_b32_e64 v147, v17, v19, s[44:45]
	s_nop 1
	v_mov_b32_dpp v146, v145 quad_perm:[2,3,0,1] row_mask:0xf bank_mask:0xf
	v_mov_b32_dpp v156, v147 quad_perm:[2,3,0,1] row_mask:0xf bank_mask:0xf
; __device__ __forceinline__ void hg_seq(const Frame& F, unsigned char* ws, const float* s0, float* sout, float* Og, int seq, bool sample, int vs_base, int nvs) {
;     ...
;     if (sample && active) {
; #pragma unroll
;         for (int kb = 0; kb < 8; ++kb)
; #pragma unroll
;             for (int i = 0; i < 4; ++i) S[kb][i] = s0[((size_t)seq * 128 + 16 * kb + 4 * q + i) * 128 + 16 * vs + r];
;     ...
;     if (active) {
; #pragma unroll
;     for (int kb = 0; kb < 8; ++kb)
; #pragma unroll
;         for (int i = 0; i < 4; ++i) sout[((size_t)seq * 128 + 16 * kb + 4 * q + i) * 128 + 16 * vs + r] = S[kb][i];
;     }
	v_cndmask_b32_e64 v18, v18, v146, s[44:45]
	v_cndmask_b32_e64 v16, v146, v16, s[44:45]
	v_cndmask_b32_e64 v19, v19, v156, s[44:45]
	v_cndmask_b32_e64 v17, v156, v17, s[44:45]
	v_cndmask_b32_e64 v145, v20, v21, s[42:43]
	v_cndmask_b32_e64 v147, v22, v23, s[42:43]
	s_nop 1
	v_mov_b32_dpp v146, v145 quad_perm:[1,0,3,2] row_mask:0xf bank_mask:0xf
	v_mov_b32_dpp v156, v147 quad_perm:[1,0,3,2] row_mask:0xf bank_mask:0xf
	v_cndmask_b32_e64 v21, v21, v146, s[42:43]
	v_cndmask_b32_e64 v20, v146, v20, s[42:43]
	v_cndmask_b32_e64 v23, v23, v156, s[42:43]
	v_cndmask_b32_e64 v22, v156, v22, s[42:43]
	v_cndmask_b32_e64 v145, v20, v22, s[44:45]
	v_cndmask_b32_e64 v147, v21, v23, s[44:45]
	s_nop 1
	v_mov_b32_dpp v146, v145 quad_perm:[2,3,0,1] row_mask:0xf bank_mask:0xf
	v_mov_b32_dpp v156, v147 quad_perm:[2,3,0,1] row_mask:0xf bank_mask:0xf
	v_cndmask_b32_e64 v22, v22, v146, s[44:45]
	v_cndmask_b32_e64 v20, v146, v20, s[44:45]
	v_cndmask_b32_e64 v23, v23, v156, s[44:45]
	v_cndmask_b32_e64 v21, v156, v21, s[44:45]
	v_cndmask_b32_e64 v145, v24, v25, s[42:43]
	v_cndmask_b32_e64 v147, v26, v27, s[42:43]
	s_nop 1
	v_mov_b32_dpp v146, v145 quad_perm:[1,0,3,2] row_mask:0xf bank_mask:0xf
	v_mov_b32_dpp v156, v147 quad_perm:[1,0,3,2] row_mask:0xf bank_mask:0xf
	v_cndmask_b32_e64 v25, v25, v146, s[42:43]
	v_cndmask_b32_e64 v24, v146, v24, s[42:43]
	v_cndmask_b32_e64 v27, v27, v156, s[42:43]
	v_cndmask_b32_e64 v26, v156, v26, s[42:43]
	v_cndmask_b32_e64 v145, v24, v26, s[44:45]
	v_cndmask_b32_e64 v147, v25, v27, s[44:45]
	s_nop 1
	v_mov_b32_dpp v146, v145 quad_perm:[2,3,0,1] row_mask:0xf bank_mask:0xf
	v_mov_b32_dpp v156, v147 quad_perm:[2,3,0,1] row_mask:0xf bank_mask:0xf
	v_cndmask_b32_e64 v26, v26, v146, s[44:45]
	v_cndmask_b32_e64 v24, v146, v24, s[44:45]
	v_cndmask_b32_e64 v27, v27, v156, s[44:45]
	v_cndmask_b32_e64 v25, v156, v25, s[44:45]
	v_cndmask_b32_e64 v145, v28, v29, s[42:43]
	v_cndmask_b32_e64 v147, v30, v31, s[42:43]
	s_nop 1
	v_mov_b32_dpp v146, v145 quad_perm:[1,0,3,2] row_mask:0xf bank_mask:0xf
	v_mov_b32_dpp v156, v147 quad_perm:[1,0,3,2] row_mask:0xf bank_mask:0xf
	v_cndmask_b32_e64 v29, v29, v146, s[42:43]
	v_cndmask_b32_e64 v28, v146, v28, s[42:43]
	v_cndmask_b32_e64 v31, v31, v156, s[42:43]
	v_cndmask_b32_e64 v30, v156, v30, s[42:43]
	v_cndmask_b32_e64 v145, v28, v30, s[44:45]
	v_cndmask_b32_e64 v147, v29, v31, s[44:45]
	s_nop 1
	v_mov_b32_dpp v146, v145 quad_perm:[2,3,0,1] row_mask:0xf bank_mask:0xf
	v_mov_b32_dpp v156, v147 quad_perm:[2,3,0,1] row_mask:0xf bank_mask:0xf
	v_cndmask_b32_e64 v30, v30, v146, s[44:45]
	v_cndmask_b32_e64 v28, v146, v28, s[44:45]
	v_cndmask_b32_e64 v31, v31, v156, s[44:45]
	v_cndmask_b32_e64 v29, v156, v29, s[44:45]
	v_cndmask_b32_e64 v145, v32, v33, s[42:43]
	v_cndmask_b32_e64 v147, v34, v35, s[42:43]
	s_nop 1
	v_mov_b32_dpp v146, v145 quad_perm:[1,0,3,2] row_mask:0xf bank_mask:0xf
	v_mov_b32_dpp v156, v147 quad_perm:[1,0,3,2] row_mask:0xf bank_mask:0xf
	v_cndmask_b32_e64 v33, v33, v146, s[42:43]
	v_cndmask_b32_e64 v32, v146, v32, s[42:43]
	v_cndmask_b32_e64 v35, v35, v156, s[42:43]
	v_cndmask_b32_e64 v34, v156, v34, s[42:43]
	v_cndmask_b32_e64 v145, v32, v34, s[44:45]
	v_cndmask_b32_e64 v147, v33, v35, s[44:45]
	s_nop 1
	v_mov_b32_dpp v146, v145 quad_perm:[2,3,0,1] row_mask:0xf bank_mask:0xf
	v_mov_b32_dpp v156, v147 quad_perm:[2,3,0,1] row_mask:0xf bank_mask:0xf
	v_cndmask_b32_e64 v34, v34, v146, s[44:45]
	v_cndmask_b32_e64 v32, v146, v32, s[44:45]
	v_cndmask_b32_e64 v35, v35, v156, s[44:45]
	v_cndmask_b32_e64 v33, v156, v33, s[44:45]
	global_store_dwordx4 v200, v[4:7], s[10:11]
	global_store_dwordx4 v201, v[8:11], s[10:11]
	global_store_dwordx4 v202, v[12:15], s[10:11]
	global_store_dwordx4 v203, v[16:19], s[10:11]
	global_store_dwordx4 v204, v[20:23], s[10:11]
	global_store_dwordx4 v205, v[24:27], s[10:11]
	global_store_dwordx4 v206, v[28:31], s[10:11]
	global_store_dwordx4 v207, v[32:35], s[10:11]
	s_add_u32 s10, s10, s34
	s_addc_u32 s11, s11, 0
	s_waitcnt vmcnt(12)
	v_cndmask_b32_e64 v145, v36, v37, s[42:43]
	v_cndmask_b32_e64 v147, v38, v39, s[42:43]
	s_nop 1
	v_mov_b32_dpp v146, v145 quad_perm:[1,0,3,2] row_mask:0xf bank_mask:0xf
	v_mov_b32_dpp v156, v147 quad_perm:[1,0,3,2] row_mask:0xf bank_mask:0xf
	v_cndmask_b32_e64 v37, v37, v146, s[42:43]
	v_cndmask_b32_e64 v36, v146, v36, s[42:43]
	v_cndmask_b32_e64 v39, v39, v156, s[42:43]
	v_cndmask_b32_e64 v38, v156, v38, s[42:43]
	v_cndmask_b32_e64 v145, v36, v38, s[44:45]
	v_cndmask_b32_e64 v147, v37, v39, s[44:45]
	s_nop 1
	v_mov_b32_dpp v146, v145 quad_perm:[2,3,0,1] row_mask:0xf bank_mask:0xf
	v_mov_b32_dpp v156, v147 quad_perm:[2,3,0,1] row_mask:0xf bank_mask:0xf
	v_cndmask_b32_e64 v38, v38, v146, s[44:45]
	v_cndmask_b32_e64 v36, v146, v36, s[44:45]
	v_cndmask_b32_e64 v39, v39, v156, s[44:45]
	v_cndmask_b32_e64 v37, v156, v37, s[44:45]
	v_cndmask_b32_e64 v145, v40, v41, s[42:43]
	v_cndmask_b32_e64 v147, v42, v43, s[42:43]
	s_nop 1
	v_mov_b32_dpp v146, v145 quad_perm:[1,0,3,2] row_mask:0xf bank_mask:0xf
	v_mov_b32_dpp v156, v147 quad_perm:[1,0,3,2] row_mask:0xf bank_mask:0xf
	v_cndmask_b32_e64 v41, v41, v146, s[42:43]
	v_cndmask_b32_e64 v40, v146, v40, s[42:43]
	v_cndmask_b32_e64 v43, v43, v156, s[42:43]
	v_cndmask_b32_e64 v42, v156, v42, s[42:43]
	v_cndmask_b32_e64 v145, v40, v42, s[44:45]
	v_cndmask_b32_e64 v147, v41, v43, s[44:45]
	s_nop 1
	v_mov_b32_dpp v146, v145 quad_perm:[2,3,0,1] row_mask:0xf bank_mask:0xf
	v_mov_b32_dpp v156, v147 quad_perm:[2,3,0,1] row_mask:0xf bank_mask:0xf
	v_cndmask_b32_e64 v42, v42, v146, s[44:45]
	v_cndmask_b32_e64 v40, v146, v40, s[44:45]
	v_cndmask_b32_e64 v43, v43, v156, s[44:45]
	v_cndmask_b32_e64 v41, v156, v41, s[44:45]
; #define LAS __attribute__((address_space(3)))
; __device__ __forceinline__ unsigned pk2(float lo, float hi) { const f32x2_t_ v = {lo, hi}; return __builtin_bit_cast(unsigned, __builtin_convertvector(v, bf16x2_t_)); }
; __device__ __forceinline__ void hg_chunk(const LAS unsigned char* sl, f32x4 (&S)[8], float* Orow, int nvalid, int vs, int lane) {
;     const int r = lane & 15, q = lane >> 4;
;     const bf16x8 vfr = *(const LAS bf16x8*)(sl + 16384 + ((vs * 64 + lane) << 4));
;     f32x4 o0 = {0.f, 0.f, 0.f, 0.f}, o1 = {0.f, 0.f, 0.f, 0.f};
;     { const bf16x8 s0 = *(const LAS bf16x8*)(sl + 24576 + (lane << 4)), s1 = *(const LAS bf16x8*)(sl + 24576 + ((64 + lane) << 4));
;       o0 = __builtin_amdgcn_mfma_f32_16x16x32_bf16(s0, vfr, o0, 0, 0, 0); o1 = __builtin_amdgcn_mfma_f32_16x16x32_bf16(s1, vfr, o1, 0, 0, 0); }
; #pragma unroll
;     for (int m = 0; m < 4; ++m) {
;         v4u sw; sw.x = pk2(S[2 * m][0], S[2 * m][1]); sw.y = pk2(S[2 * m][2], S[2 * m][3]); sw.z = pk2(S[2 * m + 1][0], S[2 * m + 1][1]); sw.w = pk2(S[2 * m + 1][2], S[2 * m + 1][3]);
;         const bf16x8 sb = __builtin_bit_cast(bf16x8, sw);
;         const bf16x8 a0 = *(const LAS bf16x8*)(sl + ((m * 64 + lane) << 4)), a1 = *(const LAS bf16x8*)(sl + (((4 + m) * 64 + lane) << 4));
;         o0 = __builtin_amdgcn_mfma_f32_16x16x32_bf16(a0, sb, o0, 0, 0, 0); o1 = __builtin_amdgcn_mfma_f32_16x16x32_bf16(a1, sb, o1, 0, 0, 0);
;     }
	v_cndmask_b32_e64 v145, v44, v45, s[42:43]
	v_cndmask_b32_e64 v147, v46, v47, s[42:43]
	s_nop 1
	v_mov_b32_dpp v146, v145 quad_perm:[1,0,3,2] row_mask:0xf bank_mask:0xf
	v_mov_b32_dpp v156, v147 quad_perm:[1,0,3,2] row_mask:0xf bank_mask:0xf
	v_cndmask_b32_e64 v45, v45, v146, s[42:43]
	v_cndmask_b32_e64 v44, v146, v44, s[42:43]
	v_cndmask_b32_e64 v47, v47, v156, s[42:43]
	v_cndmask_b32_e64 v46, v156, v46, s[42:43]
	v_cndmask_b32_e64 v145, v44, v46, s[44:45]
	v_cndmask_b32_e64 v147, v45, v47, s[44:45]
	s_nop 1
	v_mov_b32_dpp v146, v145 quad_perm:[2,3,0,1] row_mask:0xf bank_mask:0xf
	v_mov_b32_dpp v156, v147 quad_perm:[2,3,0,1] row_mask:0xf bank_mask:0xf
	v_cndmask_b32_e64 v46, v46, v146, s[44:45]
	v_cndmask_b32_e64 v44, v146, v44, s[44:45]
	v_cndmask_b32_e64 v47, v47, v156, s[44:45]
	v_cndmask_b32_e64 v45, v156, v45, s[44:45]
	v_cndmask_b32_e64 v145, v48, v49, s[42:43]
	v_cndmask_b32_e64 v147, v50, v51, s[42:43]
	s_nop 1
	v_mov_b32_dpp v146, v145 quad_perm:[1,0,3,2] row_mask:0xf bank_mask:0xf
	v_mov_b32_dpp v156, v147 quad_perm:[1,0,3,2] row_mask:0xf bank_mask:0xf
	v_cndmask_b32_e64 v49, v49, v146, s[42:43]
	v_cndmask_b32_e64 v48, v146, v48, s[42:43]
	v_cndmask_b32_e64 v51, v51, v156, s[42:43]
	v_cndmask_b32_e64 v50, v156, v50, s[42:43]
	v_cndmask_b32_e64 v145, v48, v50, s[44:45]
	v_cndmask_b32_e64 v147, v49, v51, s[44:45]
	s_nop 1
	v_mov_b32_dpp v146, v145 quad_perm:[2,3,0,1] row_mask:0xf bank_mask:0xf
	v_mov_b32_dpp v156, v147 quad_perm:[2,3,0,1] row_mask:0xf bank_mask:0xf
	v_cndmask_b32_e64 v50, v50, v146, s[44:45]
	v_cndmask_b32_e64 v48, v146, v48, s[44:45]
	v_cndmask_b32_e64 v51, v51, v156, s[44:45]
	v_cndmask_b32_e64 v49, v156, v49, s[44:45]
	v_cndmask_b32_e64 v145, v52, v53, s[42:43]
	v_cndmask_b32_e64 v147, v54, v55, s[42:43]
	s_nop 1
	v_mov_b32_dpp v146, v145 quad_perm:[1,0,3,2] row_mask:0xf bank_mask:0xf
	v_mov_b32_dpp v156, v147 quad_perm:[1,0,3,2] row_mask:0xf bank_mask:0xf
	v_cndmask_b32_e64 v53, v53, v146, s[42:43]
	v_cndmask_b32_e64 v52, v146, v52, s[42:43]
	v_cndmask_b32_e64 v55, v55, v156, s[42:43]
	v_cndmask_b32_e64 v54, v156, v54, s[42:43]
	v_cndmask_b32_e64 v145, v52, v54, s[44:45]
	v_cndmask_b32_e64 v147, v53, v55, s[44:45]
	s_nop 1
	v_mov_b32_dpp v146, v145 quad_perm:[2,3,0,1] row_mask:0xf bank_mask:0xf
	v_mov_b32_dpp v156, v147 quad_perm:[2,3,0,1] row_mask:0xf bank_mask:0xf
	v_cndmask_b32_e64 v54, v54, v146, s[44:45]
	v_cndmask_b32_e64 v52, v146, v52, s[44:45]
	v_cndmask_b32_e64 v55, v55, v156, s[44:45]
	v_cndmask_b32_e64 v53, v156, v53, s[44:45]
	v_cndmask_b32_e64 v145, v56, v57, s[42:43]
	v_cndmask_b32_e64 v147, v58, v59, s[42:43]
	s_nop 1
	v_mov_b32_dpp v146, v145 quad_perm:[1,0,3,2] row_mask:0xf bank_mask:0xf
	v_mov_b32_dpp v156, v147 quad_perm:[1,0,3,2] row_mask:0xf bank_mask:0xf
	v_cndmask_b32_e64 v57, v57, v146, s[42:43]
	v_cndmask_b32_e64 v56, v146, v56, s[42:43]
	v_cndmask_b32_e64 v59, v59, v156, s[42:43]
	v_cndmask_b32_e64 v58, v156, v58, s[42:43]
	v_cndmask_b32_e64 v145, v56, v58, s[44:45]
	v_cndmask_b32_e64 v147, v57, v59, s[44:45]
	s_nop 1
	v_mov_b32_dpp v146, v145 quad_perm:[2,3,0,1] row_mask:0xf bank_mask:0xf
	v_mov_b32_dpp v156, v147 quad_perm:[2,3,0,1] row_mask:0xf bank_mask:0xf
	v_cndmask_b32_e64 v58, v58, v146, s[44:45]
	v_cndmask_b32_e64 v56, v146, v56, s[44:45]
	v_cndmask_b32_e64 v59, v59, v156, s[44:45]
	v_cndmask_b32_e64 v57, v156, v57, s[44:45]
	v_cndmask_b32_e64 v145, v60, v61, s[42:43]
	v_cndmask_b32_e64 v147, v62, v63, s[42:43]
	s_nop 1
	v_mov_b32_dpp v146, v145 quad_perm:[1,0,3,2] row_mask:0xf bank_mask:0xf
	v_mov_b32_dpp v156, v147 quad_perm:[1,0,3,2] row_mask:0xf bank_mask:0xf
	v_cndmask_b32_e64 v61, v61, v146, s[42:43]
	v_cndmask_b32_e64 v60, v146, v60, s[42:43]
	v_cndmask_b32_e64 v63, v63, v156, s[42:43]
	v_cndmask_b32_e64 v62, v156, v62, s[42:43]
	v_cndmask_b32_e64 v145, v60, v62, s[44:45]
	v_cndmask_b32_e64 v147, v61, v63, s[44:45]
	s_nop 1
	v_mov_b32_dpp v146, v145 quad_perm:[2,3,0,1] row_mask:0xf bank_mask:0xf
	v_mov_b32_dpp v156, v147 quad_perm:[2,3,0,1] row_mask:0xf bank_mask:0xf
	v_cndmask_b32_e64 v62, v62, v146, s[44:45]
	v_cndmask_b32_e64 v60, v146, v60, s[44:45]
	v_cndmask_b32_e64 v63, v63, v156, s[44:45]
	v_cndmask_b32_e64 v61, v156, v61, s[44:45]
	v_cndmask_b32_e64 v145, v64, v65, s[42:43]
	v_cndmask_b32_e64 v147, v66, v67, s[42:43]
	s_nop 1
	v_mov_b32_dpp v146, v145 quad_perm:[1,0,3,2] row_mask:0xf bank_mask:0xf
	v_mov_b32_dpp v156, v147 quad_perm:[1,0,3,2] row_mask:0xf bank_mask:0xf
	v_cndmask_b32_e64 v65, v65, v146, s[42:43]
	v_cndmask_b32_e64 v64, v146, v64, s[42:43]
	v_cndmask_b32_e64 v67, v67, v156, s[42:43]
	v_cndmask_b32_e64 v66, v156, v66, s[42:43]
	v_cndmask_b32_e64 v145, v64, v66, s[44:45]
	v_cndmask_b32_e64 v147, v65, v67, s[44:45]
	s_nop 1
	v_mov_b32_dpp v146, v145 quad_perm:[2,3,0,1] row_mask:0xf bank_mask:0xf
	v_mov_b32_dpp v156, v147 quad_perm:[2,3,0,1] row_mask:0xf bank_mask:0xf
	v_cndmask_b32_e64 v66, v66, v146, s[44:45]
	v_cndmask_b32_e64 v64, v146, v64, s[44:45]
	v_cndmask_b32_e64 v67, v67, v156, s[44:45]
	v_cndmask_b32_e64 v65, v156, v65, s[44:45]
	v_add_u32_e32 v1, 0x14400, v142
	v_add_u32_e32 v2, 0x14400, v143
	v_add_u32_e32 v3, 0x14400, v144
	ds_read_b128 v[164:167], v3 offset:26624
	ds_read_b128 v[168:171], v3 offset:26688
	ds_read_b128 v[172:175], v3 offset:26752
	ds_read_b128 v[176:179], v3 offset:26816
	ds_read_b128 v[180:183], v3 offset:26880
	ds_read_b128 v[184:187], v3 offset:26944
	ds_read_b128 v[148:151], v3 offset:27008
	ds_read_b128 v[152:155], v3 offset:27072
	ds_read_b128 v[84:87], v2 offset:16384
	ds_read_b128 v[88:91], v1 offset:24576
	ds_read_b128 v[92:95], v1 offset:0
	ds_read_b128 v[96:99], v1 offset:1024
	ds_read_b128 v[100:103], v1 offset:2048
	ds_read_b128 v[104:107], v1 offset:3072
	v_cvt_pk_bf16_f32 v68, v36, v37
	v_cvt_pk_bf16_f32 v69, v38, v39
	v_cvt_pk_bf16_f32 v70, v40, v41
	v_cvt_pk_bf16_f32 v71, v42, v43
	v_cvt_pk_bf16_f32 v72, v44, v45
	v_cvt_pk_bf16_f32 v73, v46, v47
	v_cvt_pk_bf16_f32 v74, v48, v49
	v_cvt_pk_bf16_f32 v75, v50, v51
	v_cvt_pk_bf16_f32 v76, v52, v53
	v_cvt_pk_bf16_f32 v77, v54, v55
	v_cvt_pk_bf16_f32 v78, v56, v57
	v_cvt_pk_bf16_f32 v79, v58, v59
	v_cvt_pk_bf16_f32 v80, v60, v61
	v_cvt_pk_bf16_f32 v81, v62, v63
	v_cvt_pk_bf16_f32 v82, v64, v65
	v_cvt_pk_bf16_f32 v83, v66, v67
	s_waitcnt lgkmcnt(6)
; #define LAS __attribute__((address_space(3)))
; __device__ __forceinline__ unsigned pk2(float lo, float hi) { const f32x2_t_ v = {lo, hi}; return __builtin_bit_cast(unsigned, __builtin_convertvector(v, bf16x2_t_)); }
; __device__ __forceinline__ void hg_chunk(const LAS unsigned char* sl, f32x4 (&S)[8], float* Orow, int nvalid, int vs, int lane) {
;     const int r = lane & 15, q = lane >> 4;
;     const bf16x8 vfr = *(const LAS bf16x8*)(sl + 16384 + ((vs * 64 + lane) << 4));
;     f32x4 o0 = {0.f, 0.f, 0.f, 0.f}, o1 = {0.f, 0.f, 0.f, 0.f};
;     { const bf16x8 s0 = *(const LAS bf16x8*)(sl + 24576 + (lane << 4)), s1 = *(const LAS bf16x8*)(sl + 24576 + ((64 + lane) << 4));
;       o0 = __builtin_amdgcn_mfma_f32_16x16x32_bf16(s0, vfr, o0, 0, 0, 0); o1 = __builtin_amdgcn_mfma_f32_16x16x32_bf16(s1, vfr, o1, 0, 0, 0); }
; #pragma unroll
;     for (int m = 0; m < 4; ++m) {
;         v4u sw; sw.x = pk2(S[2 * m][0], S[2 * m][1]); sw.y = pk2(S[2 * m][2], S[2 * m][3]); sw.z = pk2(S[2 * m + 1][0], S[2 * m + 1][1]); sw.w = pk2(S[2 * m + 1][2], S[2 * m + 1][3]);
;         const bf16x8 sb = __builtin_bit_cast(bf16x8, sw);
;         const bf16x8 a0 = *(const LAS bf16x8*)(sl + ((m * 64 + lane) << 4)), a1 = *(const LAS bf16x8*)(sl + (((4 + m) * 64 + lane) << 4));
;         o0 = __builtin_amdgcn_mfma_f32_16x16x32_bf16(a0, sb, o0, 0, 0, 0); o1 = __builtin_amdgcn_mfma_f32_16x16x32_bf16(a1, sb, o1, 0, 0, 0);
;     }
; #pragma unroll
;     for (int i = 0; i < 4; ++i) { const int c0 = 4 * q + i;
;         if (c0 < nvalid) Orow[(size_t)c0 * DA + 16 * vs + r] = o0[i];
;         if (c0 + 16 < nvalid) Orow[(size_t)(c0 + 16) * DA + 16 * vs + r] = o1[i]; }
; #pragma unroll
;     for (int kb = 0; kb < 8; ++kb) { const f32x4 d = *(const LAS f32x4*)(sl + 26624 + ((16 * kb + 4 * q) << 2));
;         const bf16x8 ke = *(const LAS bf16x8*)(sl + 8192 + ((kb * 64 + lane) << 4));
;         S[kb] = __builtin_amdgcn_mfma_f32_16x16x32_bf16(ke, vfr, S[kb] * d, 0, 0, 0); }
	v_pk_mul_f32 v[36:37], v[36:37], v[164:165]
	v_pk_mul_f32 v[38:39], v[38:39], v[166:167]
	v_pk_mul_f32 v[40:41], v[40:41], v[168:169]
	v_pk_mul_f32 v[42:43], v[42:43], v[170:171]
	v_pk_mul_f32 v[44:45], v[44:45], v[172:173]
	v_pk_mul_f32 v[46:47], v[46:47], v[174:175]
	v_pk_mul_f32 v[48:49], v[48:49], v[176:177]
	v_pk_mul_f32 v[50:51], v[50:51], v[178:179]
	v_pk_mul_f32 v[52:53], v[52:53], v[180:181]
	v_pk_mul_f32 v[54:55], v[54:55], v[182:183]
	v_pk_mul_f32 v[56:57], v[56:57], v[184:185]
	v_pk_mul_f32 v[58:59], v[58:59], v[186:187]
	v_pk_mul_f32 v[60:61], v[60:61], v[148:149]
	v_pk_mul_f32 v[62:63], v[62:63], v[150:151]
	v_pk_mul_f32 v[64:65], v[64:65], v[152:153]
	v_pk_mul_f32 v[66:67], v[66:67], v[154:155]
	ds_read_b128 v[108:111], v1 offset:8192
	ds_read_b128 v[112:115], v1 offset:9216
	ds_read_b128 v[116:119], v1 offset:10240
	ds_read_b128 v[120:123], v1 offset:11264
	ds_read_b128 v[124:127], v1 offset:12288
	ds_read_b128 v[128:131], v1 offset:13312
	ds_read_b128 v[132:135], v1 offset:14336
	ds_read_b128 v[136:139], v1 offset:15360
	s_waitcnt lgkmcnt(12)
	v_mfma_f32_16x16x32_bf16 v[196:199], v[88:91], v[84:87], 0
	s_waitcnt lgkmcnt(11)
	v_mfma_f32_16x16x32_bf16 v[196:199], v[92:95], v[68:71], v[196:199]
	s_waitcnt lgkmcnt(10)
	v_mfma_f32_16x16x32_bf16 v[196:199], v[96:99], v[72:75], v[196:199]
	s_waitcnt lgkmcnt(9)
	v_mfma_f32_16x16x32_bf16 v[196:199], v[100:103], v[76:79], v[196:199]
	s_waitcnt lgkmcnt(8)
	v_mfma_f32_16x16x32_bf16 v[196:199], v[104:107], v[80:83], v[196:199]
	s_waitcnt lgkmcnt(7)
	v_mfma_f32_16x16x32_bf16 v[36:39], v[108:111], v[84:87], v[36:39]
	s_waitcnt lgkmcnt(6)
	v_mfma_f32_16x16x32_bf16 v[40:43], v[112:115], v[84:87], v[40:43]
	s_waitcnt lgkmcnt(5)
	v_mfma_f32_16x16x32_bf16 v[44:47], v[116:119], v[84:87], v[44:47]
	s_waitcnt lgkmcnt(4)
	v_mfma_f32_16x16x32_bf16 v[48:51], v[120:123], v[84:87], v[48:51]
	s_waitcnt lgkmcnt(3)
	v_mfma_f32_16x16x32_bf16 v[52:55], v[124:127], v[84:87], v[52:55]
	s_waitcnt lgkmcnt(2)
	v_mfma_f32_16x16x32_bf16 v[56:59], v[128:131], v[84:87], v[56:59]
	s_waitcnt lgkmcnt(1)
	v_mfma_f32_16x16x32_bf16 v[60:63], v[132:135], v[84:87], v[60:63]
	s_waitcnt lgkmcnt(0)
	v_mfma_f32_16x16x32_bf16 v[64:67], v[136:139], v[84:87], v[64:67]
	s_mov_b32 exec_hi, 0
	global_store_dword v208, v196, s[12:13]
	global_store_dword v208, v197, s[12:13] offset:2048
	global_store_dword v209, v198, s[12:13]
	global_store_dword v209, v199, s[12:13] offset:2048
	s_mov_b64 exec, -1
	s_add_u32 s12, s12, 0x80000
	s_addc_u32 s13, s13, 0
	s_nop 7
	v_cndmask_b32_e64 v145, v36, v37, s[42:43]
	v_cndmask_b32_e64 v147, v38, v39, s[42:43]
	s_nop 1
	v_mov_b32_dpp v146, v145 quad_perm:[1,0,3,2] row_mask:0xf bank_mask:0xf
	v_mov_b32_dpp v156, v147 quad_perm:[1,0,3,2] row_mask:0xf bank_mask:0xf
	v_cndmask_b32_e64 v37, v37, v146, s[42:43]
	v_cndmask_b32_e64 v36, v146, v36, s[42:43]
	v_cndmask_b32_e64 v39, v39, v156, s[42:43]
	v_cndmask_b32_e64 v38, v156, v38, s[42:43]
	v_cndmask_b32_e64 v145, v36, v38, s[44:45]
	v_cndmask_b32_e64 v147, v37, v39, s[44:45]
	s_nop 1
	v_mov_b32_dpp v146, v145 quad_perm:[2,3,0,1] row_mask:0xf bank_mask:0xf
	v_mov_b32_dpp v156, v147 quad_perm:[2,3,0,1] row_mask:0xf bank_mask:0xf
	v_cndmask_b32_e64 v38, v38, v146, s[44:45]
	v_cndmask_b32_e64 v36, v146, v36, s[44:45]
	v_cndmask_b32_e64 v39, v39, v156, s[44:45]
	v_cndmask_b32_e64 v37, v156, v37, s[44:45]
	v_cndmask_b32_e64 v145, v40, v41, s[42:43]
	v_cndmask_b32_e64 v147, v42, v43, s[42:43]
	s_nop 1
	v_mov_b32_dpp v146, v145 quad_perm:[1,0,3,2] row_mask:0xf bank_mask:0xf
	v_mov_b32_dpp v156, v147 quad_perm:[1,0,3,2] row_mask:0xf bank_mask:0xf
	v_cndmask_b32_e64 v41, v41, v146, s[42:43]
	v_cndmask_b32_e64 v40, v146, v40, s[42:43]
	v_cndmask_b32_e64 v43, v43, v156, s[42:43]
	v_cndmask_b32_e64 v42, v156, v42, s[42:43]
	v_cndmask_b32_e64 v145, v40, v42, s[44:45]
	v_cndmask_b32_e64 v147, v41, v43, s[44:45]
	s_nop 1
	v_mov_b32_dpp v146, v145 quad_perm:[2,3,0,1] row_mask:0xf bank_mask:0xf
	v_mov_b32_dpp v156, v147 quad_perm:[2,3,0,1] row_mask:0xf bank_mask:0xf
	v_cndmask_b32_e64 v42, v42, v146, s[44:45]
	v_cndmask_b32_e64 v40, v146, v40, s[44:45]
	v_cndmask_b32_e64 v43, v43, v156, s[44:45]
	v_cndmask_b32_e64 v41, v156, v41, s[44:45]
	v_cndmask_b32_e64 v145, v44, v45, s[42:43]
	v_cndmask_b32_e64 v147, v46, v47, s[42:43]
	s_nop 1
	v_mov_b32_dpp v146, v145 quad_perm:[1,0,3,2] row_mask:0xf bank_mask:0xf
	v_mov_b32_dpp v156, v147 quad_perm:[1,0,3,2] row_mask:0xf bank_mask:0xf
	v_cndmask_b32_e64 v45, v45, v146, s[42:43]
	v_cndmask_b32_e64 v44, v146, v44, s[42:43]
	v_cndmask_b32_e64 v47, v47, v156, s[42:43]
	v_cndmask_b32_e64 v46, v156, v46, s[42:43]
	v_cndmask_b32_e64 v145, v44, v46, s[44:45]
	v_cndmask_b32_e64 v147, v45, v47, s[44:45]
	s_nop 1
	v_mov_b32_dpp v146, v145 quad_perm:[2,3,0,1] row_mask:0xf bank_mask:0xf
	v_mov_b32_dpp v156, v147 quad_perm:[2,3,0,1] row_mask:0xf bank_mask:0xf
; #define LDSBAR() do { asm volatile("s_waitcnt lgkmcnt(0)" ::: "memory"); __builtin_amdgcn_s_barrier(); asm volatile("" ::: "memory"); } while (0)
; __device__ __forceinline__ void hg_seq(const Frame& F, unsigned char* ws, const float* s0, float* sout, float* Og, int seq, bool sample, int vs_base, int nvs) {
;     ...
;     if (active) {
; #pragma unroll
;     for (int kb = 0; kb < 8; ++kb)
; #pragma unroll
;         for (int i = 0; i < 4; ++i) sout[((size_t)seq * 128 + 16 * kb + 4 * q + i) * 128 + 16 * vs + r] = S[kb][i];
;     }
;     LDSBAR();
	v_cndmask_b32_e64 v46, v46, v146, s[44:45]
	v_cndmask_b32_e64 v44, v146, v44, s[44:45]
	v_cndmask_b32_e64 v47, v47, v156, s[44:45]
	v_cndmask_b32_e64 v45, v156, v45, s[44:45]
	v_cndmask_b32_e64 v145, v48, v49, s[42:43]
	v_cndmask_b32_e64 v147, v50, v51, s[42:43]
	s_nop 1
	v_mov_b32_dpp v146, v145 quad_perm:[1,0,3,2] row_mask:0xf bank_mask:0xf
	v_mov_b32_dpp v156, v147 quad_perm:[1,0,3,2] row_mask:0xf bank_mask:0xf
	v_cndmask_b32_e64 v49, v49, v146, s[42:43]
	v_cndmask_b32_e64 v48, v146, v48, s[42:43]
	v_cndmask_b32_e64 v51, v51, v156, s[42:43]
	v_cndmask_b32_e64 v50, v156, v50, s[42:43]
	v_cndmask_b32_e64 v145, v48, v50, s[44:45]
	v_cndmask_b32_e64 v147, v49, v51, s[44:45]
	s_nop 1
	v_mov_b32_dpp v146, v145 quad_perm:[2,3,0,1] row_mask:0xf bank_mask:0xf
	v_mov_b32_dpp v156, v147 quad_perm:[2,3,0,1] row_mask:0xf bank_mask:0xf
	v_cndmask_b32_e64 v50, v50, v146, s[44:45]
	v_cndmask_b32_e64 v48, v146, v48, s[44:45]
	v_cndmask_b32_e64 v51, v51, v156, s[44:45]
	v_cndmask_b32_e64 v49, v156, v49, s[44:45]
	v_cndmask_b32_e64 v145, v52, v53, s[42:43]
	v_cndmask_b32_e64 v147, v54, v55, s[42:43]
	s_nop 1
	v_mov_b32_dpp v146, v145 quad_perm:[1,0,3,2] row_mask:0xf bank_mask:0xf
	v_mov_b32_dpp v156, v147 quad_perm:[1,0,3,2] row_mask:0xf bank_mask:0xf
	v_cndmask_b32_e64 v53, v53, v146, s[42:43]
	v_cndmask_b32_e64 v52, v146, v52, s[42:43]
	v_cndmask_b32_e64 v55, v55, v156, s[42:43]
	v_cndmask_b32_e64 v54, v156, v54, s[42:43]
	v_cndmask_b32_e64 v145, v52, v54, s[44:45]
	v_cndmask_b32_e64 v147, v53, v55, s[44:45]
	s_nop 1
	v_mov_b32_dpp v146, v145 quad_perm:[2,3,0,1] row_mask:0xf bank_mask:0xf
	v_mov_b32_dpp v156, v147 quad_perm:[2,3,0,1] row_mask:0xf bank_mask:0xf
	v_cndmask_b32_e64 v54, v54, v146, s[44:45]
	v_cndmask_b32_e64 v52, v146, v52, s[44:45]
	v_cndmask_b32_e64 v55, v55, v156, s[44:45]
	v_cndmask_b32_e64 v53, v156, v53, s[44:45]
	v_cndmask_b32_e64 v145, v56, v57, s[42:43]
	v_cndmask_b32_e64 v147, v58, v59, s[42:43]
	s_nop 1
	v_mov_b32_dpp v146, v145 quad_perm:[1,0,3,2] row_mask:0xf bank_mask:0xf
	v_mov_b32_dpp v156, v147 quad_perm:[1,0,3,2] row_mask:0xf bank_mask:0xf
	v_cndmask_b32_e64 v57, v57, v146, s[42:43]
	v_cndmask_b32_e64 v56, v146, v56, s[42:43]
	v_cndmask_b32_e64 v59, v59, v156, s[42:43]
	v_cndmask_b32_e64 v58, v156, v58, s[42:43]
	v_cndmask_b32_e64 v145, v56, v58, s[44:45]
	v_cndmask_b32_e64 v147, v57, v59, s[44:45]
	s_nop 1
	v_mov_b32_dpp v146, v145 quad_perm:[2,3,0,1] row_mask:0xf bank_mask:0xf
	v_mov_b32_dpp v156, v147 quad_perm:[2,3,0,1] row_mask:0xf bank_mask:0xf
	v_cndmask_b32_e64 v58, v58, v146, s[44:45]
	v_cndmask_b32_e64 v56, v146, v56, s[44:45]
	v_cndmask_b32_e64 v59, v59, v156, s[44:45]
	v_cndmask_b32_e64 v57, v156, v57, s[44:45]
	v_cndmask_b32_e64 v145, v60, v61, s[42:43]
	v_cndmask_b32_e64 v147, v62, v63, s[42:43]
	s_nop 1
	v_mov_b32_dpp v146, v145 quad_perm:[1,0,3,2] row_mask:0xf bank_mask:0xf
	v_mov_b32_dpp v156, v147 quad_perm:[1,0,3,2] row_mask:0xf bank_mask:0xf
	v_cndmask_b32_e64 v61, v61, v146, s[42:43]
	v_cndmask_b32_e64 v60, v146, v60, s[42:43]
	v_cndmask_b32_e64 v63, v63, v156, s[42:43]
	v_cndmask_b32_e64 v62, v156, v62, s[42:43]
	v_cndmask_b32_e64 v145, v60, v62, s[44:45]
	v_cndmask_b32_e64 v147, v61, v63, s[44:45]
	s_nop 1
	v_mov_b32_dpp v146, v145 quad_perm:[2,3,0,1] row_mask:0xf bank_mask:0xf
	v_mov_b32_dpp v156, v147 quad_perm:[2,3,0,1] row_mask:0xf bank_mask:0xf
	v_cndmask_b32_e64 v62, v62, v146, s[44:45]
	v_cndmask_b32_e64 v60, v146, v60, s[44:45]
	v_cndmask_b32_e64 v63, v63, v156, s[44:45]
	v_cndmask_b32_e64 v61, v156, v61, s[44:45]
	v_cndmask_b32_e64 v145, v64, v65, s[42:43]
	v_cndmask_b32_e64 v147, v66, v67, s[42:43]
	s_nop 1
	v_mov_b32_dpp v146, v145 quad_perm:[1,0,3,2] row_mask:0xf bank_mask:0xf
	v_mov_b32_dpp v156, v147 quad_perm:[1,0,3,2] row_mask:0xf bank_mask:0xf
	v_cndmask_b32_e64 v65, v65, v146, s[42:43]
	v_cndmask_b32_e64 v64, v146, v64, s[42:43]
	v_cndmask_b32_e64 v67, v67, v156, s[42:43]
	v_cndmask_b32_e64 v66, v156, v66, s[42:43]
	v_cndmask_b32_e64 v145, v64, v66, s[44:45]
	v_cndmask_b32_e64 v147, v65, v67, s[44:45]
	s_nop 1
	v_mov_b32_dpp v146, v145 quad_perm:[2,3,0,1] row_mask:0xf bank_mask:0xf
	v_mov_b32_dpp v156, v147 quad_perm:[2,3,0,1] row_mask:0xf bank_mask:0xf
	v_cndmask_b32_e64 v66, v66, v146, s[44:45]
	v_cndmask_b32_e64 v64, v146, v64, s[44:45]
	v_cndmask_b32_e64 v67, v67, v156, s[44:45]
	v_cndmask_b32_e64 v65, v156, v65, s[44:45]
	global_store_dwordx4 v200, v[36:39], s[10:11]
	global_store_dwordx4 v201, v[40:43], s[10:11]
	global_store_dwordx4 v202, v[44:47], s[10:11]
	global_store_dwordx4 v203, v[48:51], s[10:11]
	global_store_dwordx4 v204, v[52:55], s[10:11]
	global_store_dwordx4 v205, v[56:59], s[10:11]
	global_store_dwordx4 v206, v[60:63], s[10:11]
	global_store_dwordx4 v207, v[64:67], s[10:11]
	s_add_u32 s10, s10, s34
	s_addc_u32 s11, s11, 0
	s_waitcnt lgkmcnt(0)
	s_barrier
	s_branch .LBB0_1245

; #define LAS __attribute__((address_space(3)))
; #define LDSBAR() do { asm volatile("s_waitcnt lgkmcnt(0)" ::: "memory"); __builtin_amdgcn_s_barrier(); asm volatile("" ::: "memory"); } while (0)
; __device__ __forceinline__ void hg_seq(const Frame& F, unsigned char* ws, const float* s0, float* sout, float* Og, int seq, bool sample, int vs_base, int nvs) {
;     LAS unsigned char* ring = F.lds;
;     const int tid = F.tid, lane = F.lane, vs = vs_base + F.wave, r = lane & 15, q = lane >> 4;
;     const bool active = F.wave < nvs, vload = (unsigned)((tid >> 6) - vs_base) < (unsigned)nvs;
;     int nch, nvalid, t0, h; const unsigned char *qf, *vf, *lf; int qp, lp; size_t qstep, lstep;
;     if (!sample) { const int b = seq >> 2; h = seq & 3; t0 = b * 2048; nch = 64; nvalid = 32; const size_t e0 = (size_t)t0 * DA + h * 128;
;         qf = ws + WS_Q + e0 * 2; vf = ws + WS_V + e0 * 2; lf = ws + WS_LOGF + e0 * 4; qp = 1024; lp = 2048; qstep = 32 * 1024; lstep = 32 * 2048; }
;     else { const int b = seq >> 2; h = seq & 3; t0 = TP + b * 8; nch = 1; nvalid = 8; const unsigned char* base = (const unsigned char*)sout + (size_t)seq * 65536;
;         qf = base; vf = base + 8192; lf = base + 16384; qp = 256; lp = 512; qstep = 0; lstep = 0; }
;     const size_t offq = (size_t)(tid >> 4) * qp + (tid & 15) * 16, offl0 = (size_t)(tid >> 5) * lp + (tid & 31) * 16, offl1 = (size_t)(16 + (tid >> 5)) * lp + (tid & 31) * 16, offl1c = tid < 160 ? offl1 : offl0;
;     {
;     f32x4 S[8];
;     if (sample && active) {
; #pragma unroll
;         for (int kb = 0; kb < 8; ++kb)
; #pragma unroll
;             for (int i = 0; i < 4; ++i) S[kb][i] = s0[((size_t)seq * 128 + 16 * kb + 4 * q + i) * 128 + 16 * vs + r];
;     } else {
; #pragma unroll
;         for (int kb = 0; kb < 8; ++kb) S[kb] = (f32x4){0.f, 0.f, 0.f, 0.f};
;     }
;     float* Ob = Og + (size_t)t0 * DA + h * 128;
;     ...
;     HgPre R0, R1, R2, R3, R4, R5;
;     R0.l1 = R0.v = (v4u){0u, 0u, 0u, 0u}; R1.l1 = R1.v = (v4u){0u, 0u, 0u, 0u}; R2.l1 = R2.v = (v4u){0u, 0u, 0u, 0u}; R3.l1 = R3.v = (v4u){0u, 0u, 0u, 0u}; R4.l1 = R4.v = (v4u){0u, 0u, 0u, 0u}; R5.l1 = R5.v = (v4u){0u, 0u, 0u, 0u};
;     HG_LOAD(R0, 0); HG_LOAD(R1, 1); HG_LOAD(R2, 2); HG_LOAD(R3, 3); HG_LOAD(R4, 4);
;     HG_STORE(R0, 0); LDSBAR();
.Lscan_entry:
	s_mov_b64 exec, -1
	s_and_b32 s6, s2, 7
	s_lshr_b32 s7, s2, 5
	s_bfe_u32 s8, s2, 0x20003
	s_lshl_b32 s8, s8, 1
	s_lshl_b32 s9, s6, 21
	s_lshl_b32 s3, s7, 8
	s_add_u32 s9, s9, s3
	s_add_u32 s10, s22, s9
	s_addc_u32 s11, s23, 0
	s_lshl_b32 s9, s9, 1
	s_add_u32 s12, s22, s9
	s_addc_u32 s13, s23, 0
	s_add_u32 s14, s10, 0xb980000
	s_addc_u32 s15, s11, 0
	s_add_u32 s16, s10, 0xca80000
	s_addc_u32 s17, s11, 0
	s_add_u32 s34, s12, 0xdb80000
	s_addc_u32 s35, s13, 0
	s_add_u32 s36, s12, 0x2080000
	s_addc_u32 s37, s13, 0
	s_mov_b32 s62, 0
	s_cmp_lt_u32 s50, 2
	s_cbranch_scc0 .Lscan_loader
	v_lshlrev_b32_e32 v160, 4, v189
	s_lshl_b32 s3, s50, 10
	v_add_u32_e32 v161, s3, v160
	v_lshrrev_b32_e32 v1, 4, v189
	v_lshlrev_b32_e32 v163, 4, v1
	s_add_i32 s3, s8, s50
	s_lshl_b32 s3, s3, 4
	v_and_b32_e32 v2, 15, v189
	v_add_u32_e32 v2, s3, v2
	v_lshlrev_b32_e32 v2, 2, v2
	v_lshl_add_u32 v172, v1, 13, v2
	v_add_u32_e32 v173, 0x1000, v172
	v_add_u32_e32 v174, 0x8000, v172
	v_add_u32_e32 v175, 0x9000, v172
	v_lshl_add_u32 v176, v1, 11, v2
	v_mov_b32_e32 v4, 0
	v_mov_b32_e32 v5, 0
	v_mov_b32_e32 v6, 0
	v_mov_b32_e32 v7, 0
	v_mov_b32_e32 v8, 0
	v_mov_b32_e32 v9, 0
	v_mov_b32_e32 v10, 0
	v_mov_b32_e32 v11, 0
	v_mov_b32_e32 v12, 0
	v_mov_b32_e32 v13, 0
	v_mov_b32_e32 v14, 0
	v_mov_b32_e32 v15, 0
	v_mov_b32_e32 v16, 0
	v_mov_b32_e32 v17, 0
	v_mov_b32_e32 v18, 0
	v_mov_b32_e32 v19, 0
	v_mov_b32_e32 v20, 0
	v_mov_b32_e32 v21, 0
	v_mov_b32_e32 v22, 0
	v_mov_b32_e32 v23, 0
	v_mov_b32_e32 v24, 0
	v_mov_b32_e32 v25, 0
	v_mov_b32_e32 v26, 0
	v_mov_b32_e32 v27, 0
	v_mov_b32_e32 v28, 0
	v_mov_b32_e32 v29, 0
	v_mov_b32_e32 v30, 0
	v_mov_b32_e32 v31, 0
	v_mov_b32_e32 v32, 0
	v_mov_b32_e32 v33, 0
	v_mov_b32_e32 v34, 0
	v_mov_b32_e32 v35, 0
	s_mov_b32 s60, 0
	s_barrier

; #define LDSBAR() do { asm volatile("s_waitcnt lgkmcnt(0)" ::: "memory"); __builtin_amdgcn_s_barrier(); asm volatile("" ::: "memory"); } while (0)
; #define HG_STORE(R, s) do { LAS unsigned char* d_ = ring + (s) * HG_SLOT; *(LAS v4u*)(d_ + 16 * tid) = R.q; if (vload) *(LAS v4u*)(d_ + 16384 + 16 * tid) = R.v; *(LAS v4u*)(d_ + 8192 + 16 * tid) = R.l0; \
;         if (tid < 160) *(LAS v4u*)(d_ + 24576 + 16 * tid) = R.l1; } while (0)
; __device__ __forceinline__ void hg_seq(const Frame& F, unsigned char* ws, const float* s0, float* sout, float* Og, int seq, bool sample, int vs_base, int nvs) {
;     ...
;     for (int n = 0; n < nch; n += 6) {
;         HG_LOAD(R5, n + 5); if (active) hg_chunk(ring, S, Ob + (size_t)(n + 0) * 32 * DA, nvalid, vs, lane); if (n + 1 < nch) HG_STORE(R1, 1); LDSBAR(); if (n + 1 >= nch) break;
;         HG_LOAD(R0, n + 6); if (active) hg_chunk(ring + HG_SLOT, S, Ob + (size_t)(n + 1) * 32 * DA, nvalid, vs, lane); if (n + 2 < nch) HG_STORE(R2, 0); LDSBAR(); if (n + 2 >= nch) break;
;         HG_LOAD(R1, n + 7); if (active) hg_chunk(ring, S, Ob + (size_t)(n + 2) * 32 * DA, nvalid, vs, lane); if (n + 3 < nch) HG_STORE(R3, 1); LDSBAR(); if (n + 3 >= nch) break;
;         HG_LOAD(R2, n + 8); if (active) hg_chunk(ring + HG_SLOT, S, Ob + (size_t)(n + 3) * 32 * DA, nvalid, vs, lane); if (n + 4 < nch) HG_STORE(R4, 0); LDSBAR(); if (n + 4 >= nch) break;
;         HG_LOAD(R3, n + 9); if (active) hg_chunk(ring, S, Ob + (size_t)(n + 4) * 32 * DA, nvalid, vs, lane); if (n + 5 < nch) HG_STORE(R5, 1); LDSBAR(); if (n + 5 >= nch) break;
;         HG_LOAD(R4, n + 10); if (active) hg_chunk(ring + HG_SLOT, S, Ob + (size_t)(n + 5) * 32 * DA, nvalid, vs, lane); if (n + 6 < nch) HG_STORE(R0, 0); LDSBAR();
;     }
.Lscan_noadv_556:
	s_add_i32 s60, s60, 21504
	s_cmp_lt_u32 s60, 129024
	s_cselect_b32 s60, s60, 0
	s_add_i32 s62, s62, 1
	s_waitcnt vmcnt(16)
	s_barrier
	s_cmp_lt_u32 s62, 64
	s_cbranch_scc1 .Lscan_ld_loop
	s_waitcnt vmcnt(0)
.Lscan_join:
	s_branch .Lsmp_entry
.LBB0_1245:
	s_waitcnt lgkmcnt(0)
	s_barrier
